# scanner: y-partial reduction software-pipelined into the following steps (reads split over two steps, adds as fillers), one first-step variant per half-chunk
# baseline (speedup 1.0000x reference)
; template <int CTRL> __device__ __forceinline__ float dppf(float x) { return __builtin_bit_cast(float, __builtin_amdgcn_update_dpp(0, __builtin_bit_cast(int, x), CTRL, 0xF, 0xF, false)); }
; __device__ __forceinline__ void phase_rwkv_scan(const Fr& F, int jr) {
;     ...
;             {
;                 float* Ypw = Yp + wave * 1024;
;                 unsigned a1 = (unsigned)(size_t)(__attribute__((address_space(3))) float*)(Wv + ks), a2 = (unsigned)(size_t)(__attribute__((address_space(3))) float*)(Rr + ks),
;                          a3 = (unsigned)(size_t)(__attribute__((address_space(3))) float*)(Vv + rloc), a4 = (unsigned)(size_t)(__attribute__((address_space(3))) float*)(Ypw + lane);
;                 asm volatile("" : "+v"(a1), "+v"(a2), "+v"(a3), "+v"(a4));
;                 typedef const __attribute__((address_space(3))) f32x4* lp4; typedef const __attribute__((address_space(3))) float* lp1; typedef __attribute__((address_space(3))) float* lw1;
;                 const lp4 PW = (lp4)a1, PR = (lp4)a2; const lp1 PV = (lp1)a3; const lw1 PY = (lw1)a4;
;                 f32x4 w4 = PW[0], k4 = PW[1024], b4 = PW[2048], d4 = PW[3072], r4 = PR[0];
;                 float vv = PV[0];
;                 for (int pg = 0; pg < 64; pg += 16) {
; #pragma unroll
;                     for (int pi = 0; pi < 16; ++pi) {
;                         const int p = pg + pi, pn = p < 63 ? p + 1 : 63;
;                         const f32x4 w4n = PW[pn * 16], k4n = PW[1024 + pn * 16], b4n = PW[2048 + pn * 16], d4n = PW[3072 + pn * 16], r4n = PR[pn * 16];
;                         const float vvn = PV[pn * 32];
;                         f32x2 t = S01 * k4.xy; t = S23 * k4.zw + t; float sa = t.x + t.y;
;                         sa += dppf<0x128>(sa);
;                         const f32x2 dv01 = d4.xy * vv, dv23 = d4.zw * vv;
;                         sa += dppf<0x124>(sa);
;                         const f32x2 e01 = S01 * w4.xy + dv01;
;                         sa += dppf<0x122>(sa);
;                         const f32x2 e23 = S23 * w4.zw + dv23;
;                         sa += dppf<0x121>(sa);
;                         S01 = e01 - b4.xy * sa; S23 = e23 - b4.zw * sa;
;                         f32x2 u = S01 * r4.xy; u = S23 * r4.zw + u;
;                         PY[pi * 64] = u.x + u.y;
;                         w4 = w4n; k4 = k4n; b4 = b4n; d4 = d4n; r4 = r4n; vv = vvn;
.Lrw0_sdir0:
	v_and_b32_e32 v243, 3, v130
	s_lshl_b32 s16, s68, 4
	v_lshl_add_u32 v220, v243, 2, s16
	s_mul_i32 s16, s6, 0x2200000
	s_add_u32 s20, s26, s16
	s_addc_u32 s21, s27, 0
	s_add_u32 s20, s20, 0x1200000
	s_addc_u32 s21, s21, 0
	s_mul_i32 s16, s7, 0x880000
	s_add_u32 s20, s20, s16
	s_addc_u32 s21, s21, 0
	s_and_b32 s16, s3, 31
	s_lshl_b32 s16, s16, 6
	s_add_u32 s20, s20, s16
	s_addc_u32 s21, s21, 0
	s_mov_b32 s10, 0
	s_mov_b32 s11, 0
	s_mov_b32 s15, 0
	v_mov_b32_e32 v222, 0
	v_mov_b32_e32 v223, 0
	v_mov_b32_e32 v224, 0
	v_mov_b32_e32 v225, 0
	s_waitcnt lgkmcnt(0)
	s_barrier
.Lrw0_shc:
	v_add_u32_e32 v240, s11, v214
	v_add_u32_e32 v242, s11, v216
	ds_read_b128 v[84:87], v240 offset:8704
	ds_read_b64 v[100:101], v242 offset:43520
	ds_read_b128 v[92:95], v240 offset:26112
	ds_read_b128 v[80:83], v240 offset:0
	ds_read_b128 v[88:91], v240 offset:17408
	ds_read_b128 v[96:99], v240 offset:34816
	v_pk_mul_f32 v[228:229], v[206:207], v[222:223] op_sel_hi:[1,0]
	v_pk_fma_f32 v[228:229], v[208:209], v[222:223], v[228:229] op_sel:[0,1,0]
	v_pk_fma_f32 v[228:229], v[210:211], v[224:225], v[228:229] op_sel_hi:[1,0,1]
	v_pk_fma_f32 v[228:229], v[212:213], v[224:225], v[228:229] op_sel:[0,1,0]
	s_mov_b32 s87, s15
	s_lshl_b32 s17, s10, 5
	s_cmp_lt_u32 s10, 8
	s_movk_i32 s18, 0x11ff
	s_cselect_b32 s18, 0xff, s18
	s_sub_i32 s18, s18, s17
	s_cmp_eq_u32 s6, 0
	s_cselect_b32 s15, s17, s18
	s_cselect_b32 s19, 16, -16
	ds_write_b64 v217, v[228:229] offset:8640
	s_waitcnt lgkmcnt(2)
	ds_read_b128 v[106:109], v240 offset:8976
	ds_read_b64 v[118:119], v242 offset:43792
	ds_read_b128 v[114:117], v240 offset:26384
	ds_read_b128 v[102:105], v240 offset:272
	ds_read_b128 v[110:113], v240 offset:17680
	ds_read_b128 v[0:3], v218 offset:0
	ds_read_b128 v[4:7], v218 offset:16
	ds_read_b128 v[8:11], v218 offset:32
	ds_read_b128 v[12:15], v218 offset:48
	v_pk_mul_f32 v[226:227], v[206:207], v[84:85] op_sel_hi:[1,0]
	v_pk_mul_f32 v[232:233], v[100:101], v[92:93] op_sel_hi:[1,0]
	v_pk_fma_f32 v[226:227], v[208:209], v[84:85], v[226:227] op_sel:[0,1,0]
	v_pk_mul_f32 v[234:235], v[100:101], v[92:93] op_sel:[0,1]
	v_pk_fma_f32 v[226:227], v[210:211], v[86:87], v[226:227] op_sel_hi:[1,0,1]
	v_pk_mul_f32 v[236:237], v[100:101], v[94:95] op_sel_hi:[1,0]
	v_pk_fma_f32 v[226:227], v[212:213], v[86:87], v[226:227] op_sel:[0,1,0]
	v_pk_mul_f32 v[238:239], v[100:101], v[94:95] op_sel:[0,1]
	s_nop 0
	v_add_f32_dpp v230, v227, v226 row_ror:8 row_mask:0xf bank_mask:0xf
	v_pk_fma_f32 v[232:233], v[206:207], v[80:81], v[232:233] op_sel_hi:[1,0,1]
	v_pk_fma_f32 v[234:235], v[208:209], v[80:81], v[234:235] op_sel:[0,1,0]
	v_add_f32_dpp v230, v230, v230 quad_perm:[1,0,3,2] row_mask:0xf bank_mask:0xf
	v_pk_fma_f32 v[236:237], v[210:211], v[82:83], v[236:237] op_sel_hi:[1,0,1]
	v_pk_fma_f32 v[238:239], v[212:213], v[82:83], v[238:239] op_sel:[0,1,0]
	v_add_f32_dpp v230, v230, v230 quad_perm:[2,3,0,1] row_mask:0xf bank_mask:0xf
	ds_read_b128 v[222:225], v240 offset:35088
	s_nop 0
	v_add_f32_dpp v230, v230, v230 row_half_mirror row_mask:0xf bank_mask:0xf
	s_nop 1
	v_mov_b32_dpp v231, v230 row_ror:8 row_mask:0xf bank_mask:0xf
	s_nop 0
	v_pk_fma_f32 v[206:207], v[88:89], v[230:231], v[232:233] op_sel_hi:[0,1,1] neg_lo:[1,0,0] neg_hi:[1,0,0]
	v_pk_fma_f32 v[208:209], v[88:89], v[230:231], v[234:235] op_sel:[1,0,0] neg_lo:[1,0,0] neg_hi:[1,0,0]
	v_pk_fma_f32 v[210:211], v[90:91], v[230:231], v[236:237] op_sel_hi:[0,1,1] neg_lo:[1,0,0] neg_hi:[1,0,0]
	v_pk_fma_f32 v[212:213], v[90:91], v[230:231], v[238:239] op_sel:[1,0,0] neg_lo:[1,0,0] neg_hi:[1,0,0]
	s_waitcnt lgkmcnt(5)
	ds_read_b128 v[84:87], v240 offset:9248
	ds_read_b64 v[100:101], v242 offset:44064
	ds_read_b128 v[92:95], v240 offset:26656
	ds_read_b128 v[80:83], v240 offset:544
	ds_read_b128 v[88:91], v240 offset:17952
	ds_read_b128 v[16:19], v218 offset:64
	ds_read_b128 v[20:23], v218 offset:80
	ds_read_b128 v[24:27], v218 offset:96
	ds_read_b128 v[28:31], v218 offset:112
	v_pk_mul_f32 v[226:227], v[206:207], v[106:107] op_sel_hi:[1,0]
	v_pk_mul_f32 v[228:229], v[206:207], v[96:97] op_sel_hi:[1,0]
	v_pk_fma_f32 v[226:227], v[208:209], v[106:107], v[226:227] op_sel:[0,1,0]
	v_pk_fma_f32 v[228:229], v[208:209], v[96:97], v[228:229] op_sel:[0,1,0]
	v_pk_fma_f32 v[226:227], v[210:211], v[108:109], v[226:227] op_sel_hi:[1,0,1]
	v_pk_fma_f32 v[228:229], v[210:211], v[98:99], v[228:229] op_sel_hi:[1,0,1]
	v_pk_fma_f32 v[226:227], v[212:213], v[108:109], v[226:227] op_sel:[0,1,0]
	v_pk_fma_f32 v[228:229], v[212:213], v[98:99], v[228:229] op_sel:[0,1,0]
	v_pk_mul_f32 v[232:233], v[118:119], v[114:115] op_sel_hi:[1,0]
	v_add_f32_dpp v230, v227, v226 row_ror:8 row_mask:0xf bank_mask:0xf
	v_pk_mul_f32 v[234:235], v[118:119], v[114:115] op_sel:[0,1]
	v_pk_mul_f32 v[236:237], v[118:119], v[116:117] op_sel_hi:[1,0]
	v_add_f32_dpp v230, v230, v230 quad_perm:[1,0,3,2] row_mask:0xf bank_mask:0xf
	v_pk_mul_f32 v[238:239], v[118:119], v[116:117] op_sel:[0,1]
	s_waitcnt lgkmcnt(10)
	ds_read_b128 v[96:99], v240 offset:35360
	v_add_f32_dpp v230, v230, v230 quad_perm:[2,3,0,1] row_mask:0xf bank_mask:0xf
	v_pk_fma_f32 v[232:233], v[206:207], v[102:103], v[232:233] op_sel_hi:[1,0,1]
	v_pk_fma_f32 v[234:235], v[208:209], v[102:103], v[234:235] op_sel:[0,1,0]
	v_add_f32_dpp v230, v230, v230 row_half_mirror row_mask:0xf bank_mask:0xf
	v_pk_fma_f32 v[236:237], v[210:211], v[104:105], v[236:237] op_sel_hi:[1,0,1]
	v_pk_fma_f32 v[238:239], v[212:213], v[104:105], v[238:239] op_sel:[0,1,0]
	v_mov_b32_dpp v231, v230 row_ror:8 row_mask:0xf bank_mask:0xf
	ds_write_b64 v217, v[228:229] offset:0
	v_pk_fma_f32 v[206:207], v[110:111], v[230:231], v[232:233] op_sel_hi:[0,1,1] neg_lo:[1,0,0] neg_hi:[1,0,0]
	v_pk_fma_f32 v[208:209], v[110:111], v[230:231], v[234:235] op_sel:[1,0,0] neg_lo:[1,0,0] neg_hi:[1,0,0]
	v_pk_fma_f32 v[210:211], v[112:113], v[230:231], v[236:237] op_sel_hi:[0,1,1] neg_lo:[1,0,0] neg_hi:[1,0,0]
	v_pk_fma_f32 v[212:213], v[112:113], v[230:231], v[238:239] op_sel:[1,0,0] neg_lo:[1,0,0] neg_hi:[1,0,0]
	s_waitcnt lgkmcnt(6)
; __device__ __forceinline__ unsigned f2bf(float f) { unsigned u = __builtin_bit_cast(unsigned, f); return (u + 0x7fffu + ((u >> 16) & 1u)) >> 16; }
; template <int CTRL> __device__ __forceinline__ float dppf(float x) { return __builtin_bit_cast(float, __builtin_amdgcn_update_dpp(0, __builtin_bit_cast(int, x), CTRL, 0xF, 0xF, false)); }
; __device__ __forceinline__ void phase_rwkv_scan(const Fr& F, int jr) {
;     ...
;                 for (int pg = 0; pg < 64; pg += 16) {
; #pragma unroll
;                     for (int pi = 0; pi < 16; ++pi) {
;                         const int p = pg + pi, pn = p < 63 ? p + 1 : 63;
;                         const f32x4 w4n = PW[pn * 16], k4n = PW[1024 + pn * 16], b4n = PW[2048 + pn * 16], d4n = PW[3072 + pn * 16], r4n = PR[pn * 16];
;                         const float vvn = PV[pn * 32];
;                         f32x2 t = S01 * k4.xy; t = S23 * k4.zw + t; float sa = t.x + t.y;
;                         sa += dppf<0x128>(sa);
;                         const f32x2 dv01 = d4.xy * vv, dv23 = d4.zw * vv;
;                         sa += dppf<0x124>(sa);
;                         const f32x2 e01 = S01 * w4.xy + dv01;
;                         sa += dppf<0x122>(sa);
;                         const f32x2 e23 = S23 * w4.zw + dv23;
;                         sa += dppf<0x121>(sa);
;                         S01 = e01 - b4.xy * sa; S23 = e23 - b4.zw * sa;
;                         f32x2 u = S01 * r4.xy; u = S23 * r4.zw + u;
;                         PY[pi * 64] = u.x + u.y;
;                         w4 = w4n; k4 = k4n; b4 = b4n; d4 = d4n; r4 = r4n; vv = vvn;
;                     }
;                     asm volatile("s_waitcnt lgkmcnt(0)" ::: "memory");
;                     {
;                         const int j = lane >> 2, q = lane & 3; const float* yp = Ypw + j * 64 + q * 16;
;                         const f32x4 a0 = *(const f32x4*)yp, a1 = *(const f32x4*)(yp + 4), a2 = *(const f32x4*)(yp + 8), a3 = *(const f32x4*)(yp + 12);
;                         const f32x4 ssum = (a0 + a1) + (a2 + a3); const float yv = (ssum.x + ssum.y) + (ssum.z + ssum.w);
;                         const size_t row = (size_t)b * TB + tokof(s, chunk * 64 + pg + j);
;                         Yb[row * D + h * 64 + 32 * half + 4 * wave + q] = (bf16)f2bf(yv);
;                     }
	ds_read_b128 v[106:109], v240 offset:9520
	ds_read_b64 v[118:119], v242 offset:44336
	ds_read_b128 v[114:117], v240 offset:26928
	ds_read_b128 v[102:105], v240 offset:816
	ds_read_b128 v[110:113], v240 offset:18224
	v_pk_mul_f32 v[226:227], v[206:207], v[84:85] op_sel_hi:[1,0]
	v_pk_mul_f32 v[228:229], v[206:207], v[222:223] op_sel_hi:[1,0]
	v_pk_fma_f32 v[226:227], v[208:209], v[84:85], v[226:227] op_sel:[0,1,0]
	v_pk_fma_f32 v[228:229], v[208:209], v[222:223], v[228:229] op_sel:[0,1,0]
	v_pk_fma_f32 v[226:227], v[210:211], v[86:87], v[226:227] op_sel_hi:[1,0,1]
	v_pk_fma_f32 v[228:229], v[210:211], v[224:225], v[228:229] op_sel_hi:[1,0,1]
	v_pk_fma_f32 v[226:227], v[212:213], v[86:87], v[226:227] op_sel:[0,1,0]
	v_pk_fma_f32 v[228:229], v[212:213], v[224:225], v[228:229] op_sel:[0,1,0]
	v_pk_add_f32 v[0:1], v[0:1], v[2:3]
	v_pk_mul_f32 v[232:233], v[100:101], v[92:93] op_sel_hi:[1,0]
	v_add_f32_dpp v230, v227, v226 row_ror:8 row_mask:0xf bank_mask:0xf
	v_pk_add_f32 v[4:5], v[4:5], v[6:7]
	v_pk_mul_f32 v[234:235], v[100:101], v[92:93] op_sel:[0,1]
	v_pk_mul_f32 v[236:237], v[100:101], v[94:95] op_sel_hi:[1,0]
	v_add_f32_dpp v230, v230, v230 quad_perm:[1,0,3,2] row_mask:0xf bank_mask:0xf
	v_pk_add_f32 v[8:9], v[8:9], v[10:11]
	v_pk_mul_f32 v[238:239], v[100:101], v[94:95] op_sel:[0,1]
	ds_read_b128 v[222:225], v240 offset:35632
	v_add_f32_dpp v230, v230, v230 quad_perm:[2,3,0,1] row_mask:0xf bank_mask:0xf
	v_pk_add_f32 v[12:13], v[12:13], v[14:15]
	v_pk_fma_f32 v[232:233], v[206:207], v[80:81], v[232:233] op_sel_hi:[1,0,1]
	v_pk_fma_f32 v[234:235], v[208:209], v[80:81], v[234:235] op_sel:[0,1,0]
	v_add_f32_dpp v230, v230, v230 row_half_mirror row_mask:0xf bank_mask:0xf
	v_pk_add_f32 v[0:1], v[0:1], v[4:5]
	v_pk_fma_f32 v[236:237], v[210:211], v[82:83], v[236:237] op_sel_hi:[1,0,1]
	v_pk_fma_f32 v[238:239], v[212:213], v[82:83], v[238:239] op_sel:[0,1,0]
	v_mov_b32_dpp v231, v230 row_ror:8 row_mask:0xf bank_mask:0xf
	s_waitcnt lgkmcnt(10)
	v_pk_add_f32 v[16:17], v[16:17], v[18:19]
	ds_write_b64 v217, v[228:229] offset:576
	v_pk_fma_f32 v[206:207], v[88:89], v[230:231], v[232:233] op_sel_hi:[0,1,1] neg_lo:[1,0,0] neg_hi:[1,0,0]
	v_pk_fma_f32 v[208:209], v[88:89], v[230:231], v[234:235] op_sel:[1,0,0] neg_lo:[1,0,0] neg_hi:[1,0,0]
	v_pk_add_f32 v[20:21], v[20:21], v[22:23]
	v_pk_fma_f32 v[210:211], v[90:91], v[230:231], v[236:237] op_sel_hi:[0,1,1] neg_lo:[1,0,0] neg_hi:[1,0,0]
	v_pk_fma_f32 v[212:213], v[90:91], v[230:231], v[238:239] op_sel:[1,0,0] neg_lo:[1,0,0] neg_hi:[1,0,0]
	v_pk_add_f32 v[8:9], v[8:9], v[12:13]
	s_waitcnt lgkmcnt(2)
	ds_read_b128 v[84:87], v240 offset:9792
	ds_read_b64 v[100:101], v242 offset:44608
	ds_read_b128 v[92:95], v240 offset:27200
	ds_read_b128 v[80:83], v240 offset:1088
	ds_read_b128 v[88:91], v240 offset:18496
	v_pk_mul_f32 v[226:227], v[206:207], v[106:107] op_sel_hi:[1,0]
	v_pk_mul_f32 v[228:229], v[206:207], v[96:97] op_sel_hi:[1,0]
	v_pk_fma_f32 v[226:227], v[208:209], v[106:107], v[226:227] op_sel:[0,1,0]
	v_pk_fma_f32 v[228:229], v[208:209], v[96:97], v[228:229] op_sel:[0,1,0]
	v_pk_fma_f32 v[226:227], v[210:211], v[108:109], v[226:227] op_sel_hi:[1,0,1]
	v_pk_fma_f32 v[228:229], v[210:211], v[98:99], v[228:229] op_sel_hi:[1,0,1]
	v_pk_fma_f32 v[226:227], v[212:213], v[108:109], v[226:227] op_sel:[0,1,0]
	v_pk_fma_f32 v[228:229], v[212:213], v[98:99], v[228:229] op_sel:[0,1,0]
	v_pk_add_f32 v[24:25], v[24:25], v[26:27]
	v_pk_mul_f32 v[232:233], v[118:119], v[114:115] op_sel_hi:[1,0]
	v_add_f32_dpp v230, v227, v226 row_ror:8 row_mask:0xf bank_mask:0xf
	v_pk_add_f32 v[28:29], v[28:29], v[30:31]
	v_pk_mul_f32 v[234:235], v[118:119], v[114:115] op_sel:[0,1]
	v_pk_mul_f32 v[236:237], v[118:119], v[116:117] op_sel_hi:[1,0]
	v_add_f32_dpp v230, v230, v230 quad_perm:[1,0,3,2] row_mask:0xf bank_mask:0xf
	v_pk_add_f32 v[16:17], v[16:17], v[20:21]
	v_pk_mul_f32 v[238:239], v[118:119], v[116:117] op_sel:[0,1]
	ds_read_b128 v[96:99], v240 offset:35904
	v_add_f32_dpp v230, v230, v230 quad_perm:[2,3,0,1] row_mask:0xf bank_mask:0xf
	v_pk_add_f32 v[0:1], v[0:1], v[8:9]
	v_pk_fma_f32 v[232:233], v[206:207], v[102:103], v[232:233] op_sel_hi:[1,0,1]
	v_pk_fma_f32 v[234:235], v[208:209], v[102:103], v[234:235] op_sel:[0,1,0]
	v_add_f32_dpp v230, v230, v230 row_half_mirror row_mask:0xf bank_mask:0xf
	v_pk_add_f32 v[24:25], v[24:25], v[28:29]
	v_pk_fma_f32 v[236:237], v[210:211], v[104:105], v[236:237] op_sel_hi:[1,0,1]
	v_pk_fma_f32 v[238:239], v[212:213], v[104:105], v[238:239] op_sel:[0,1,0]
	v_mov_b32_dpp v231, v230 row_ror:8 row_mask:0xf bank_mask:0xf
	v_add_u32_e32 v243, s87, v219
	ds_write_b64 v217, v[228:229] offset:1152
	v_pk_fma_f32 v[206:207], v[110:111], v[230:231], v[232:233] op_sel_hi:[0,1,1] neg_lo:[1,0,0] neg_hi:[1,0,0]
	v_pk_fma_f32 v[208:209], v[110:111], v[230:231], v[234:235] op_sel:[1,0,0] neg_lo:[1,0,0] neg_hi:[1,0,0]
	v_pk_add_f32 v[16:17], v[16:17], v[24:25]
	v_pk_fma_f32 v[210:211], v[112:113], v[230:231], v[236:237] op_sel_hi:[0,1,1] neg_lo:[1,0,0] neg_hi:[1,0,0]
	v_pk_fma_f32 v[212:213], v[112:113], v[230:231], v[238:239] op_sel:[1,0,0] neg_lo:[1,0,0] neg_hi:[1,0,0]
	v_lshl_add_u32 v243, v243, 11, v220
	s_waitcnt lgkmcnt(2)
	ds_read_b128 v[106:109], v240 offset:10064
	ds_read_b64 v[118:119], v242 offset:44880
	ds_read_b128 v[114:117], v240 offset:27472
	ds_read_b128 v[102:105], v240 offset:1360
	ds_read_b128 v[110:113], v240 offset:18768
	v_pk_mul_f32 v[226:227], v[206:207], v[84:85] op_sel_hi:[1,0]
	v_pk_mul_f32 v[228:229], v[206:207], v[222:223] op_sel_hi:[1,0]
	v_pk_fma_f32 v[226:227], v[208:209], v[84:85], v[226:227] op_sel:[0,1,0]
	v_pk_fma_f32 v[228:229], v[208:209], v[222:223], v[228:229] op_sel:[0,1,0]
	v_pk_fma_f32 v[226:227], v[210:211], v[86:87], v[226:227] op_sel_hi:[1,0,1]
	v_pk_fma_f32 v[228:229], v[210:211], v[224:225], v[228:229] op_sel_hi:[1,0,1]
	v_pk_fma_f32 v[226:227], v[212:213], v[86:87], v[226:227] op_sel:[0,1,0]
	v_pk_fma_f32 v[228:229], v[212:213], v[224:225], v[228:229] op_sel:[0,1,0]
	v_pk_add_f32 v[0:1], v[0:1], v[16:17] op_sel:[0,1] op_sel_hi:[1,0]
	v_pk_mul_f32 v[232:233], v[100:101], v[92:93] op_sel_hi:[1,0]
	v_add_f32_dpp v230, v227, v226 row_ror:8 row_mask:0xf bank_mask:0xf
	s_nop 0
	v_pk_mul_f32 v[234:235], v[100:101], v[92:93] op_sel:[0,1]
	v_pk_mul_f32 v[236:237], v[100:101], v[94:95] op_sel_hi:[1,0]
	v_add_f32_dpp v230, v230, v230 quad_perm:[1,0,3,2] row_mask:0xf bank_mask:0xf
	v_cvt_pk_bf16_f32 v244, v0, v1
	v_pk_mul_f32 v[238:239], v[100:101], v[94:95] op_sel:[0,1]
	ds_read_b128 v[222:225], v240 offset:36176
	v_add_f32_dpp v230, v230, v230 quad_perm:[2,3,0,1] row_mask:0xf bank_mask:0xf
	s_cmp_eq_u32 s10, 0
	s_cbranch_scc1 .Lrw0_nosta
	global_store_dword v243, v244, s[20:21]
; template <int CTRL> __device__ __forceinline__ float dppf(float x) { return __builtin_bit_cast(float, __builtin_amdgcn_update_dpp(0, __builtin_bit_cast(int, x), CTRL, 0xF, 0xF, false)); }
; __device__ __forceinline__ void phase_rwkv_scan(const Fr& F, int jr) {
;     ...
;                     for (int pi = 0; pi < 16; ++pi) {
;                         const int p = pg + pi, pn = p < 63 ? p + 1 : 63;
;                         const f32x4 w4n = PW[pn * 16], k4n = PW[1024 + pn * 16], b4n = PW[2048 + pn * 16], d4n = PW[3072 + pn * 16], r4n = PR[pn * 16];
;                         const float vvn = PV[pn * 32];
;                         f32x2 t = S01 * k4.xy; t = S23 * k4.zw + t; float sa = t.x + t.y;
;                         sa += dppf<0x128>(sa);
;                         const f32x2 dv01 = d4.xy * vv, dv23 = d4.zw * vv;
;                         sa += dppf<0x124>(sa);
;                         const f32x2 e01 = S01 * w4.xy + dv01;
;                         sa += dppf<0x122>(sa);
;                         const f32x2 e23 = S23 * w4.zw + dv23;
;                         sa += dppf<0x121>(sa);
;                         S01 = e01 - b4.xy * sa; S23 = e23 - b4.zw * sa;
;                         f32x2 u = S01 * r4.xy; u = S23 * r4.zw + u;
;                         PY[pi * 64] = u.x + u.y;
;                         w4 = w4n; k4 = k4n; b4 = b4n; d4 = d4n; r4 = r4n; vv = vvn;
.Lrw0_nosta:
	v_pk_fma_f32 v[232:233], v[206:207], v[80:81], v[232:233] op_sel_hi:[1,0,1]
	v_pk_fma_f32 v[234:235], v[208:209], v[80:81], v[234:235] op_sel:[0,1,0]
	v_add_f32_dpp v230, v230, v230 row_half_mirror row_mask:0xf bank_mask:0xf
	v_pk_fma_f32 v[236:237], v[210:211], v[82:83], v[236:237] op_sel_hi:[1,0,1]
	v_pk_fma_f32 v[238:239], v[212:213], v[82:83], v[238:239] op_sel:[0,1,0]
	v_mov_b32_dpp v231, v230 row_ror:8 row_mask:0xf bank_mask:0xf
	ds_write_b64 v217, v[228:229] offset:1728
	v_pk_fma_f32 v[206:207], v[88:89], v[230:231], v[232:233] op_sel_hi:[0,1,1] neg_lo:[1,0,0] neg_hi:[1,0,0]
	v_pk_fma_f32 v[208:209], v[88:89], v[230:231], v[234:235] op_sel:[1,0,0] neg_lo:[1,0,0] neg_hi:[1,0,0]
	v_pk_fma_f32 v[210:211], v[90:91], v[230:231], v[236:237] op_sel_hi:[0,1,1] neg_lo:[1,0,0] neg_hi:[1,0,0]
	v_pk_fma_f32 v[212:213], v[90:91], v[230:231], v[238:239] op_sel:[1,0,0] neg_lo:[1,0,0] neg_hi:[1,0,0]
	ds_read_b128 v[84:87], v240 offset:10336
	ds_read_b64 v[100:101], v242 offset:45152
	ds_read_b128 v[92:95], v240 offset:27744
	ds_read_b128 v[80:83], v240 offset:1632
	ds_read_b128 v[88:91], v240 offset:19040
	s_waitcnt lgkmcnt(7)
	v_pk_mul_f32 v[226:227], v[206:207], v[106:107] op_sel_hi:[1,0]
	v_pk_mul_f32 v[228:229], v[206:207], v[96:97] op_sel_hi:[1,0]
	v_pk_fma_f32 v[226:227], v[208:209], v[106:107], v[226:227] op_sel:[0,1,0]
	v_pk_fma_f32 v[228:229], v[208:209], v[96:97], v[228:229] op_sel:[0,1,0]
	v_pk_fma_f32 v[226:227], v[210:211], v[108:109], v[226:227] op_sel_hi:[1,0,1]
	v_pk_fma_f32 v[228:229], v[210:211], v[98:99], v[228:229] op_sel_hi:[1,0,1]
	v_pk_fma_f32 v[226:227], v[212:213], v[108:109], v[226:227] op_sel:[0,1,0]
	v_pk_fma_f32 v[228:229], v[212:213], v[98:99], v[228:229] op_sel:[0,1,0]
	v_pk_mul_f32 v[232:233], v[118:119], v[114:115] op_sel_hi:[1,0]
	v_add_f32_dpp v230, v227, v226 row_ror:8 row_mask:0xf bank_mask:0xf
	v_pk_mul_f32 v[234:235], v[118:119], v[114:115] op_sel:[0,1]
	v_pk_mul_f32 v[236:237], v[118:119], v[116:117] op_sel_hi:[1,0]
	v_add_f32_dpp v230, v230, v230 quad_perm:[1,0,3,2] row_mask:0xf bank_mask:0xf
	v_pk_mul_f32 v[238:239], v[118:119], v[116:117] op_sel:[0,1]
	ds_read_b128 v[96:99], v240 offset:36448
	v_add_f32_dpp v230, v230, v230 quad_perm:[2,3,0,1] row_mask:0xf bank_mask:0xf
	v_pk_fma_f32 v[232:233], v[206:207], v[102:103], v[232:233] op_sel_hi:[1,0,1]
	v_pk_fma_f32 v[234:235], v[208:209], v[102:103], v[234:235] op_sel:[0,1,0]
	v_add_f32_dpp v230, v230, v230 row_half_mirror row_mask:0xf bank_mask:0xf
	v_pk_fma_f32 v[236:237], v[210:211], v[104:105], v[236:237] op_sel_hi:[1,0,1]
	v_pk_fma_f32 v[238:239], v[212:213], v[104:105], v[238:239] op_sel:[0,1,0]
	v_mov_b32_dpp v231, v230 row_ror:8 row_mask:0xf bank_mask:0xf
	ds_write_b64 v217, v[228:229] offset:2304
	v_pk_fma_f32 v[206:207], v[110:111], v[230:231], v[232:233] op_sel_hi:[0,1,1] neg_lo:[1,0,0] neg_hi:[1,0,0]
	v_pk_fma_f32 v[208:209], v[110:111], v[230:231], v[234:235] op_sel:[1,0,0] neg_lo:[1,0,0] neg_hi:[1,0,0]
	v_pk_fma_f32 v[210:211], v[112:113], v[230:231], v[236:237] op_sel_hi:[0,1,1] neg_lo:[1,0,0] neg_hi:[1,0,0]
	v_pk_fma_f32 v[212:213], v[112:113], v[230:231], v[238:239] op_sel:[1,0,0] neg_lo:[1,0,0] neg_hi:[1,0,0]
	ds_read_b128 v[106:109], v240 offset:10608
	ds_read_b64 v[118:119], v242 offset:45424
	ds_read_b128 v[114:117], v240 offset:28016
	ds_read_b128 v[102:105], v240 offset:1904
	ds_read_b128 v[110:113], v240 offset:19312
	s_waitcnt lgkmcnt(7)
	v_pk_mul_f32 v[226:227], v[206:207], v[84:85] op_sel_hi:[1,0]
	v_pk_mul_f32 v[228:229], v[206:207], v[222:223] op_sel_hi:[1,0]
	v_pk_fma_f32 v[226:227], v[208:209], v[84:85], v[226:227] op_sel:[0,1,0]
	v_pk_fma_f32 v[228:229], v[208:209], v[222:223], v[228:229] op_sel:[0,1,0]
	v_pk_fma_f32 v[226:227], v[210:211], v[86:87], v[226:227] op_sel_hi:[1,0,1]
	v_pk_fma_f32 v[228:229], v[210:211], v[224:225], v[228:229] op_sel_hi:[1,0,1]
	v_pk_fma_f32 v[226:227], v[212:213], v[86:87], v[226:227] op_sel:[0,1,0]
	v_pk_fma_f32 v[228:229], v[212:213], v[224:225], v[228:229] op_sel:[0,1,0]
	v_pk_mul_f32 v[232:233], v[100:101], v[92:93] op_sel_hi:[1,0]
	v_add_f32_dpp v230, v227, v226 row_ror:8 row_mask:0xf bank_mask:0xf
	v_pk_mul_f32 v[234:235], v[100:101], v[92:93] op_sel:[0,1]
	v_pk_mul_f32 v[236:237], v[100:101], v[94:95] op_sel_hi:[1,0]
	v_add_f32_dpp v230, v230, v230 quad_perm:[1,0,3,2] row_mask:0xf bank_mask:0xf
	v_pk_mul_f32 v[238:239], v[100:101], v[94:95] op_sel:[0,1]
	ds_read_b128 v[222:225], v240 offset:36720
	v_add_f32_dpp v230, v230, v230 quad_perm:[2,3,0,1] row_mask:0xf bank_mask:0xf
	v_pk_fma_f32 v[232:233], v[206:207], v[80:81], v[232:233] op_sel_hi:[1,0,1]
	v_pk_fma_f32 v[234:235], v[208:209], v[80:81], v[234:235] op_sel:[0,1,0]
	v_add_f32_dpp v230, v230, v230 row_half_mirror row_mask:0xf bank_mask:0xf
	v_pk_fma_f32 v[236:237], v[210:211], v[82:83], v[236:237] op_sel_hi:[1,0,1]
	v_pk_fma_f32 v[238:239], v[212:213], v[82:83], v[238:239] op_sel:[0,1,0]
	v_mov_b32_dpp v231, v230 row_ror:8 row_mask:0xf bank_mask:0xf
	ds_write_b64 v217, v[228:229] offset:2880
	v_pk_fma_f32 v[206:207], v[88:89], v[230:231], v[232:233] op_sel_hi:[0,1,1] neg_lo:[1,0,0] neg_hi:[1,0,0]
	v_pk_fma_f32 v[208:209], v[88:89], v[230:231], v[234:235] op_sel:[1,0,0] neg_lo:[1,0,0] neg_hi:[1,0,0]
	v_pk_fma_f32 v[210:211], v[90:91], v[230:231], v[236:237] op_sel_hi:[0,1,1] neg_lo:[1,0,0] neg_hi:[1,0,0]
	v_pk_fma_f32 v[212:213], v[90:91], v[230:231], v[238:239] op_sel:[1,0,0] neg_lo:[1,0,0] neg_hi:[1,0,0]
	ds_read_b128 v[84:87], v240 offset:10880
	ds_read_b64 v[100:101], v242 offset:45696
	ds_read_b128 v[92:95], v240 offset:28288
	ds_read_b128 v[80:83], v240 offset:2176
	ds_read_b128 v[88:91], v240 offset:19584
	s_waitcnt lgkmcnt(7)
; template <int CTRL> __device__ __forceinline__ float dppf(float x) { return __builtin_bit_cast(float, __builtin_amdgcn_update_dpp(0, __builtin_bit_cast(int, x), CTRL, 0xF, 0xF, false)); }
; __device__ __forceinline__ void phase_rwkv_scan(const Fr& F, int jr) {
;     ...
;                     for (int pi = 0; pi < 16; ++pi) {
;                         const int p = pg + pi, pn = p < 63 ? p + 1 : 63;
;                         const f32x4 w4n = PW[pn * 16], k4n = PW[1024 + pn * 16], b4n = PW[2048 + pn * 16], d4n = PW[3072 + pn * 16], r4n = PR[pn * 16];
;                         const float vvn = PV[pn * 32];
;                         f32x2 t = S01 * k4.xy; t = S23 * k4.zw + t; float sa = t.x + t.y;
;                         sa += dppf<0x128>(sa);
;                         const f32x2 dv01 = d4.xy * vv, dv23 = d4.zw * vv;
;                         sa += dppf<0x124>(sa);
;                         const f32x2 e01 = S01 * w4.xy + dv01;
;                         sa += dppf<0x122>(sa);
;                         const f32x2 e23 = S23 * w4.zw + dv23;
;                         sa += dppf<0x121>(sa);
;                         S01 = e01 - b4.xy * sa; S23 = e23 - b4.zw * sa;
;                         f32x2 u = S01 * r4.xy; u = S23 * r4.zw + u;
;                         PY[pi * 64] = u.x + u.y;
;                         w4 = w4n; k4 = k4n; b4 = b4n; d4 = d4n; r4 = r4n; vv = vvn;
	v_pk_mul_f32 v[226:227], v[206:207], v[106:107] op_sel_hi:[1,0]
	v_pk_mul_f32 v[228:229], v[206:207], v[96:97] op_sel_hi:[1,0]
	v_pk_fma_f32 v[226:227], v[208:209], v[106:107], v[226:227] op_sel:[0,1,0]
	v_pk_fma_f32 v[228:229], v[208:209], v[96:97], v[228:229] op_sel:[0,1,0]
	v_pk_fma_f32 v[226:227], v[210:211], v[108:109], v[226:227] op_sel_hi:[1,0,1]
	v_pk_fma_f32 v[228:229], v[210:211], v[98:99], v[228:229] op_sel_hi:[1,0,1]
	v_pk_fma_f32 v[226:227], v[212:213], v[108:109], v[226:227] op_sel:[0,1,0]
	v_pk_fma_f32 v[228:229], v[212:213], v[98:99], v[228:229] op_sel:[0,1,0]
	v_pk_mul_f32 v[232:233], v[118:119], v[114:115] op_sel_hi:[1,0]
	v_add_f32_dpp v230, v227, v226 row_ror:8 row_mask:0xf bank_mask:0xf
	v_pk_mul_f32 v[234:235], v[118:119], v[114:115] op_sel:[0,1]
	v_pk_mul_f32 v[236:237], v[118:119], v[116:117] op_sel_hi:[1,0]
	v_add_f32_dpp v230, v230, v230 quad_perm:[1,0,3,2] row_mask:0xf bank_mask:0xf
	v_pk_mul_f32 v[238:239], v[118:119], v[116:117] op_sel:[0,1]
	ds_read_b128 v[96:99], v240 offset:36992
	v_add_f32_dpp v230, v230, v230 quad_perm:[2,3,0,1] row_mask:0xf bank_mask:0xf
	v_pk_fma_f32 v[232:233], v[206:207], v[102:103], v[232:233] op_sel_hi:[1,0,1]
	v_pk_fma_f32 v[234:235], v[208:209], v[102:103], v[234:235] op_sel:[0,1,0]
	v_add_f32_dpp v230, v230, v230 row_half_mirror row_mask:0xf bank_mask:0xf
	v_pk_fma_f32 v[236:237], v[210:211], v[104:105], v[236:237] op_sel_hi:[1,0,1]
	v_pk_fma_f32 v[238:239], v[212:213], v[104:105], v[238:239] op_sel:[0,1,0]
	v_mov_b32_dpp v231, v230 row_ror:8 row_mask:0xf bank_mask:0xf
	ds_write_b64 v217, v[228:229] offset:3456
	v_pk_fma_f32 v[206:207], v[110:111], v[230:231], v[232:233] op_sel_hi:[0,1,1] neg_lo:[1,0,0] neg_hi:[1,0,0]
	v_pk_fma_f32 v[208:209], v[110:111], v[230:231], v[234:235] op_sel:[1,0,0] neg_lo:[1,0,0] neg_hi:[1,0,0]
	v_pk_fma_f32 v[210:211], v[112:113], v[230:231], v[236:237] op_sel_hi:[0,1,1] neg_lo:[1,0,0] neg_hi:[1,0,0]
	v_pk_fma_f32 v[212:213], v[112:113], v[230:231], v[238:239] op_sel:[1,0,0] neg_lo:[1,0,0] neg_hi:[1,0,0]
	ds_read_b128 v[106:109], v240 offset:11152
	ds_read_b64 v[118:119], v242 offset:45968
	ds_read_b128 v[114:117], v240 offset:28560
	ds_read_b128 v[102:105], v240 offset:2448
	ds_read_b128 v[110:113], v240 offset:19856
	s_waitcnt lgkmcnt(7)
	v_pk_mul_f32 v[226:227], v[206:207], v[84:85] op_sel_hi:[1,0]
	v_pk_mul_f32 v[228:229], v[206:207], v[222:223] op_sel_hi:[1,0]
	v_pk_fma_f32 v[226:227], v[208:209], v[84:85], v[226:227] op_sel:[0,1,0]
	v_pk_fma_f32 v[228:229], v[208:209], v[222:223], v[228:229] op_sel:[0,1,0]
	v_pk_fma_f32 v[226:227], v[210:211], v[86:87], v[226:227] op_sel_hi:[1,0,1]
	v_pk_fma_f32 v[228:229], v[210:211], v[224:225], v[228:229] op_sel_hi:[1,0,1]
	v_pk_fma_f32 v[226:227], v[212:213], v[86:87], v[226:227] op_sel:[0,1,0]
	v_pk_fma_f32 v[228:229], v[212:213], v[224:225], v[228:229] op_sel:[0,1,0]
	v_pk_mul_f32 v[232:233], v[100:101], v[92:93] op_sel_hi:[1,0]
	v_add_f32_dpp v230, v227, v226 row_ror:8 row_mask:0xf bank_mask:0xf
	v_pk_mul_f32 v[234:235], v[100:101], v[92:93] op_sel:[0,1]
	v_pk_mul_f32 v[236:237], v[100:101], v[94:95] op_sel_hi:[1,0]
	v_add_f32_dpp v230, v230, v230 quad_perm:[1,0,3,2] row_mask:0xf bank_mask:0xf
	v_pk_mul_f32 v[238:239], v[100:101], v[94:95] op_sel:[0,1]
	ds_read_b128 v[222:225], v240 offset:37264
	v_add_f32_dpp v230, v230, v230 quad_perm:[2,3,0,1] row_mask:0xf bank_mask:0xf
	v_pk_fma_f32 v[232:233], v[206:207], v[80:81], v[232:233] op_sel_hi:[1,0,1]
	v_pk_fma_f32 v[234:235], v[208:209], v[80:81], v[234:235] op_sel:[0,1,0]
	v_add_f32_dpp v230, v230, v230 row_half_mirror row_mask:0xf bank_mask:0xf
	v_pk_fma_f32 v[236:237], v[210:211], v[82:83], v[236:237] op_sel_hi:[1,0,1]
	v_pk_fma_f32 v[238:239], v[212:213], v[82:83], v[238:239] op_sel:[0,1,0]
	v_mov_b32_dpp v231, v230 row_ror:8 row_mask:0xf bank_mask:0xf
	ds_write_b64 v217, v[228:229] offset:4032
	v_pk_fma_f32 v[206:207], v[88:89], v[230:231], v[232:233] op_sel_hi:[0,1,1] neg_lo:[1,0,0] neg_hi:[1,0,0]
	v_pk_fma_f32 v[208:209], v[88:89], v[230:231], v[234:235] op_sel:[1,0,0] neg_lo:[1,0,0] neg_hi:[1,0,0]
	v_pk_fma_f32 v[210:211], v[90:91], v[230:231], v[236:237] op_sel_hi:[0,1,1] neg_lo:[1,0,0] neg_hi:[1,0,0]
	v_pk_fma_f32 v[212:213], v[90:91], v[230:231], v[238:239] op_sel:[1,0,0] neg_lo:[1,0,0] neg_hi:[1,0,0]
	ds_read_b128 v[84:87], v240 offset:11424
	ds_read_b64 v[100:101], v242 offset:46240
	ds_read_b128 v[92:95], v240 offset:28832
	ds_read_b128 v[80:83], v240 offset:2720
	ds_read_b128 v[88:91], v240 offset:20128
	s_waitcnt lgkmcnt(7)
; template <int CTRL> __device__ __forceinline__ float dppf(float x) { return __builtin_bit_cast(float, __builtin_amdgcn_update_dpp(0, __builtin_bit_cast(int, x), CTRL, 0xF, 0xF, false)); }
; __device__ __forceinline__ void phase_rwkv_scan(const Fr& F, int jr) {
;     ...
;                     for (int pi = 0; pi < 16; ++pi) {
;                         const int p = pg + pi, pn = p < 63 ? p + 1 : 63;
;                         const f32x4 w4n = PW[pn * 16], k4n = PW[1024 + pn * 16], b4n = PW[2048 + pn * 16], d4n = PW[3072 + pn * 16], r4n = PR[pn * 16];
;                         const float vvn = PV[pn * 32];
;                         f32x2 t = S01 * k4.xy; t = S23 * k4.zw + t; float sa = t.x + t.y;
;                         sa += dppf<0x128>(sa);
;                         const f32x2 dv01 = d4.xy * vv, dv23 = d4.zw * vv;
;                         sa += dppf<0x124>(sa);
;                         const f32x2 e01 = S01 * w4.xy + dv01;
;                         sa += dppf<0x122>(sa);
;                         const f32x2 e23 = S23 * w4.zw + dv23;
;                         sa += dppf<0x121>(sa);
;                         S01 = e01 - b4.xy * sa; S23 = e23 - b4.zw * sa;
;                         f32x2 u = S01 * r4.xy; u = S23 * r4.zw + u;
;                         PY[pi * 64] = u.x + u.y;
;                         w4 = w4n; k4 = k4n; b4 = b4n; d4 = d4n; r4 = r4n; vv = vvn;
	v_pk_mul_f32 v[226:227], v[206:207], v[106:107] op_sel_hi:[1,0]
	v_pk_mul_f32 v[228:229], v[206:207], v[96:97] op_sel_hi:[1,0]
	v_pk_fma_f32 v[226:227], v[208:209], v[106:107], v[226:227] op_sel:[0,1,0]
	v_pk_fma_f32 v[228:229], v[208:209], v[96:97], v[228:229] op_sel:[0,1,0]
	v_pk_fma_f32 v[226:227], v[210:211], v[108:109], v[226:227] op_sel_hi:[1,0,1]
	v_pk_fma_f32 v[228:229], v[210:211], v[98:99], v[228:229] op_sel_hi:[1,0,1]
	v_pk_fma_f32 v[226:227], v[212:213], v[108:109], v[226:227] op_sel:[0,1,0]
	v_pk_fma_f32 v[228:229], v[212:213], v[98:99], v[228:229] op_sel:[0,1,0]
	v_pk_mul_f32 v[232:233], v[118:119], v[114:115] op_sel_hi:[1,0]
	v_add_f32_dpp v230, v227, v226 row_ror:8 row_mask:0xf bank_mask:0xf
	v_pk_mul_f32 v[234:235], v[118:119], v[114:115] op_sel:[0,1]
	v_pk_mul_f32 v[236:237], v[118:119], v[116:117] op_sel_hi:[1,0]
	v_add_f32_dpp v230, v230, v230 quad_perm:[1,0,3,2] row_mask:0xf bank_mask:0xf
	v_pk_mul_f32 v[238:239], v[118:119], v[116:117] op_sel:[0,1]
	ds_read_b128 v[96:99], v240 offset:37536
	v_add_f32_dpp v230, v230, v230 quad_perm:[2,3,0,1] row_mask:0xf bank_mask:0xf
	v_pk_fma_f32 v[232:233], v[206:207], v[102:103], v[232:233] op_sel_hi:[1,0,1]
	v_pk_fma_f32 v[234:235], v[208:209], v[102:103], v[234:235] op_sel:[0,1,0]
	v_add_f32_dpp v230, v230, v230 row_half_mirror row_mask:0xf bank_mask:0xf
	v_pk_fma_f32 v[236:237], v[210:211], v[104:105], v[236:237] op_sel_hi:[1,0,1]
	v_pk_fma_f32 v[238:239], v[212:213], v[104:105], v[238:239] op_sel:[0,1,0]
	v_mov_b32_dpp v231, v230 row_ror:8 row_mask:0xf bank_mask:0xf
	ds_write_b64 v217, v[228:229] offset:4608
	v_pk_fma_f32 v[206:207], v[110:111], v[230:231], v[232:233] op_sel_hi:[0,1,1] neg_lo:[1,0,0] neg_hi:[1,0,0]
	v_pk_fma_f32 v[208:209], v[110:111], v[230:231], v[234:235] op_sel:[1,0,0] neg_lo:[1,0,0] neg_hi:[1,0,0]
	v_pk_fma_f32 v[210:211], v[112:113], v[230:231], v[236:237] op_sel_hi:[0,1,1] neg_lo:[1,0,0] neg_hi:[1,0,0]
	v_pk_fma_f32 v[212:213], v[112:113], v[230:231], v[238:239] op_sel:[1,0,0] neg_lo:[1,0,0] neg_hi:[1,0,0]
	ds_read_b128 v[106:109], v240 offset:11696
	ds_read_b64 v[118:119], v242 offset:46512
	ds_read_b128 v[114:117], v240 offset:29104
	ds_read_b128 v[102:105], v240 offset:2992
	ds_read_b128 v[110:113], v240 offset:20400
	s_waitcnt lgkmcnt(7)
	v_pk_mul_f32 v[226:227], v[206:207], v[84:85] op_sel_hi:[1,0]
	v_pk_mul_f32 v[228:229], v[206:207], v[222:223] op_sel_hi:[1,0]
	v_pk_fma_f32 v[226:227], v[208:209], v[84:85], v[226:227] op_sel:[0,1,0]
	v_pk_fma_f32 v[228:229], v[208:209], v[222:223], v[228:229] op_sel:[0,1,0]
	v_pk_fma_f32 v[226:227], v[210:211], v[86:87], v[226:227] op_sel_hi:[1,0,1]
	v_pk_fma_f32 v[228:229], v[210:211], v[224:225], v[228:229] op_sel_hi:[1,0,1]
	v_pk_fma_f32 v[226:227], v[212:213], v[86:87], v[226:227] op_sel:[0,1,0]
	v_pk_fma_f32 v[228:229], v[212:213], v[224:225], v[228:229] op_sel:[0,1,0]
	v_pk_mul_f32 v[232:233], v[100:101], v[92:93] op_sel_hi:[1,0]
	v_add_f32_dpp v230, v227, v226 row_ror:8 row_mask:0xf bank_mask:0xf
	v_pk_mul_f32 v[234:235], v[100:101], v[92:93] op_sel:[0,1]
	v_pk_mul_f32 v[236:237], v[100:101], v[94:95] op_sel_hi:[1,0]
	v_add_f32_dpp v230, v230, v230 quad_perm:[1,0,3,2] row_mask:0xf bank_mask:0xf
	v_pk_mul_f32 v[238:239], v[100:101], v[94:95] op_sel:[0,1]
	ds_read_b128 v[222:225], v240 offset:37808
	v_add_f32_dpp v230, v230, v230 quad_perm:[2,3,0,1] row_mask:0xf bank_mask:0xf
	v_pk_fma_f32 v[232:233], v[206:207], v[80:81], v[232:233] op_sel_hi:[1,0,1]
	v_pk_fma_f32 v[234:235], v[208:209], v[80:81], v[234:235] op_sel:[0,1,0]
	v_add_f32_dpp v230, v230, v230 row_half_mirror row_mask:0xf bank_mask:0xf
	v_pk_fma_f32 v[236:237], v[210:211], v[82:83], v[236:237] op_sel_hi:[1,0,1]
	v_pk_fma_f32 v[238:239], v[212:213], v[82:83], v[238:239] op_sel:[0,1,0]
	v_mov_b32_dpp v231, v230 row_ror:8 row_mask:0xf bank_mask:0xf
	ds_write_b64 v217, v[228:229] offset:5184
	v_pk_fma_f32 v[206:207], v[88:89], v[230:231], v[232:233] op_sel_hi:[0,1,1] neg_lo:[1,0,0] neg_hi:[1,0,0]
	v_pk_fma_f32 v[208:209], v[88:89], v[230:231], v[234:235] op_sel:[1,0,0] neg_lo:[1,0,0] neg_hi:[1,0,0]
	v_pk_fma_f32 v[210:211], v[90:91], v[230:231], v[236:237] op_sel_hi:[0,1,1] neg_lo:[1,0,0] neg_hi:[1,0,0]
	v_pk_fma_f32 v[212:213], v[90:91], v[230:231], v[238:239] op_sel:[1,0,0] neg_lo:[1,0,0] neg_hi:[1,0,0]
	ds_read_b128 v[84:87], v240 offset:11968
	ds_read_b64 v[100:101], v242 offset:46784
	ds_read_b128 v[92:95], v240 offset:29376
	ds_read_b128 v[80:83], v240 offset:3264
	ds_read_b128 v[88:91], v240 offset:20672
	s_waitcnt lgkmcnt(7)
; template <int CTRL> __device__ __forceinline__ float dppf(float x) { return __builtin_bit_cast(float, __builtin_amdgcn_update_dpp(0, __builtin_bit_cast(int, x), CTRL, 0xF, 0xF, false)); }
; __device__ __forceinline__ void phase_rwkv_scan(const Fr& F, int jr) {
;     ...
;                     for (int pi = 0; pi < 16; ++pi) {
;                         const int p = pg + pi, pn = p < 63 ? p + 1 : 63;
;                         const f32x4 w4n = PW[pn * 16], k4n = PW[1024 + pn * 16], b4n = PW[2048 + pn * 16], d4n = PW[3072 + pn * 16], r4n = PR[pn * 16];
;                         const float vvn = PV[pn * 32];
;                         f32x2 t = S01 * k4.xy; t = S23 * k4.zw + t; float sa = t.x + t.y;
;                         sa += dppf<0x128>(sa);
;                         const f32x2 dv01 = d4.xy * vv, dv23 = d4.zw * vv;
;                         sa += dppf<0x124>(sa);
;                         const f32x2 e01 = S01 * w4.xy + dv01;
;                         sa += dppf<0x122>(sa);
;                         const f32x2 e23 = S23 * w4.zw + dv23;
;                         sa += dppf<0x121>(sa);
;                         S01 = e01 - b4.xy * sa; S23 = e23 - b4.zw * sa;
;                         f32x2 u = S01 * r4.xy; u = S23 * r4.zw + u;
;                         PY[pi * 64] = u.x + u.y;
;                         w4 = w4n; k4 = k4n; b4 = b4n; d4 = d4n; r4 = r4n; vv = vvn;
	v_pk_mul_f32 v[226:227], v[206:207], v[106:107] op_sel_hi:[1,0]
	v_pk_mul_f32 v[228:229], v[206:207], v[96:97] op_sel_hi:[1,0]
	v_pk_fma_f32 v[226:227], v[208:209], v[106:107], v[226:227] op_sel:[0,1,0]
	v_pk_fma_f32 v[228:229], v[208:209], v[96:97], v[228:229] op_sel:[0,1,0]
	v_pk_fma_f32 v[226:227], v[210:211], v[108:109], v[226:227] op_sel_hi:[1,0,1]
	v_pk_fma_f32 v[228:229], v[210:211], v[98:99], v[228:229] op_sel_hi:[1,0,1]
	v_pk_fma_f32 v[226:227], v[212:213], v[108:109], v[226:227] op_sel:[0,1,0]
	v_pk_fma_f32 v[228:229], v[212:213], v[98:99], v[228:229] op_sel:[0,1,0]
	v_pk_mul_f32 v[232:233], v[118:119], v[114:115] op_sel_hi:[1,0]
	v_add_f32_dpp v230, v227, v226 row_ror:8 row_mask:0xf bank_mask:0xf
	v_pk_mul_f32 v[234:235], v[118:119], v[114:115] op_sel:[0,1]
	v_pk_mul_f32 v[236:237], v[118:119], v[116:117] op_sel_hi:[1,0]
	v_add_f32_dpp v230, v230, v230 quad_perm:[1,0,3,2] row_mask:0xf bank_mask:0xf
	v_pk_mul_f32 v[238:239], v[118:119], v[116:117] op_sel:[0,1]
	ds_read_b128 v[96:99], v240 offset:38080
	v_add_f32_dpp v230, v230, v230 quad_perm:[2,3,0,1] row_mask:0xf bank_mask:0xf
	v_pk_fma_f32 v[232:233], v[206:207], v[102:103], v[232:233] op_sel_hi:[1,0,1]
	v_pk_fma_f32 v[234:235], v[208:209], v[102:103], v[234:235] op_sel:[0,1,0]
	v_add_f32_dpp v230, v230, v230 row_half_mirror row_mask:0xf bank_mask:0xf
	v_pk_fma_f32 v[236:237], v[210:211], v[104:105], v[236:237] op_sel_hi:[1,0,1]
	v_pk_fma_f32 v[238:239], v[212:213], v[104:105], v[238:239] op_sel:[0,1,0]
	v_mov_b32_dpp v231, v230 row_ror:8 row_mask:0xf bank_mask:0xf
	ds_write_b64 v217, v[228:229] offset:5760
	v_pk_fma_f32 v[206:207], v[110:111], v[230:231], v[232:233] op_sel_hi:[0,1,1] neg_lo:[1,0,0] neg_hi:[1,0,0]
	v_pk_fma_f32 v[208:209], v[110:111], v[230:231], v[234:235] op_sel:[1,0,0] neg_lo:[1,0,0] neg_hi:[1,0,0]
	v_pk_fma_f32 v[210:211], v[112:113], v[230:231], v[236:237] op_sel_hi:[0,1,1] neg_lo:[1,0,0] neg_hi:[1,0,0]
	v_pk_fma_f32 v[212:213], v[112:113], v[230:231], v[238:239] op_sel:[1,0,0] neg_lo:[1,0,0] neg_hi:[1,0,0]
	ds_read_b128 v[106:109], v240 offset:12240
	ds_read_b64 v[118:119], v242 offset:47056
	ds_read_b128 v[114:117], v240 offset:29648
	ds_read_b128 v[102:105], v240 offset:3536
	ds_read_b128 v[110:113], v240 offset:20944
	s_waitcnt lgkmcnt(7)
	v_pk_mul_f32 v[226:227], v[206:207], v[84:85] op_sel_hi:[1,0]
	v_pk_mul_f32 v[228:229], v[206:207], v[222:223] op_sel_hi:[1,0]
	v_pk_fma_f32 v[226:227], v[208:209], v[84:85], v[226:227] op_sel:[0,1,0]
	v_pk_fma_f32 v[228:229], v[208:209], v[222:223], v[228:229] op_sel:[0,1,0]
	v_pk_fma_f32 v[226:227], v[210:211], v[86:87], v[226:227] op_sel_hi:[1,0,1]
	v_pk_fma_f32 v[228:229], v[210:211], v[224:225], v[228:229] op_sel_hi:[1,0,1]
	v_pk_fma_f32 v[226:227], v[212:213], v[86:87], v[226:227] op_sel:[0,1,0]
	v_pk_fma_f32 v[228:229], v[212:213], v[224:225], v[228:229] op_sel:[0,1,0]
	v_pk_mul_f32 v[232:233], v[100:101], v[92:93] op_sel_hi:[1,0]
	v_add_f32_dpp v230, v227, v226 row_ror:8 row_mask:0xf bank_mask:0xf
	v_pk_mul_f32 v[234:235], v[100:101], v[92:93] op_sel:[0,1]
	v_pk_mul_f32 v[236:237], v[100:101], v[94:95] op_sel_hi:[1,0]
	v_add_f32_dpp v230, v230, v230 quad_perm:[1,0,3,2] row_mask:0xf bank_mask:0xf
	v_pk_mul_f32 v[238:239], v[100:101], v[94:95] op_sel:[0,1]
	ds_read_b128 v[222:225], v240 offset:38352
	v_add_f32_dpp v230, v230, v230 quad_perm:[2,3,0,1] row_mask:0xf bank_mask:0xf
	v_pk_fma_f32 v[232:233], v[206:207], v[80:81], v[232:233] op_sel_hi:[1,0,1]
	v_pk_fma_f32 v[234:235], v[208:209], v[80:81], v[234:235] op_sel:[0,1,0]
	v_add_f32_dpp v230, v230, v230 row_half_mirror row_mask:0xf bank_mask:0xf
	v_pk_fma_f32 v[236:237], v[210:211], v[82:83], v[236:237] op_sel_hi:[1,0,1]
	v_pk_fma_f32 v[238:239], v[212:213], v[82:83], v[238:239] op_sel:[0,1,0]
	v_mov_b32_dpp v231, v230 row_ror:8 row_mask:0xf bank_mask:0xf
	ds_write_b64 v217, v[228:229] offset:6336
	v_pk_fma_f32 v[206:207], v[88:89], v[230:231], v[232:233] op_sel_hi:[0,1,1] neg_lo:[1,0,0] neg_hi:[1,0,0]
	v_pk_fma_f32 v[208:209], v[88:89], v[230:231], v[234:235] op_sel:[1,0,0] neg_lo:[1,0,0] neg_hi:[1,0,0]
	v_pk_fma_f32 v[210:211], v[90:91], v[230:231], v[236:237] op_sel_hi:[0,1,1] neg_lo:[1,0,0] neg_hi:[1,0,0]
	v_pk_fma_f32 v[212:213], v[90:91], v[230:231], v[238:239] op_sel:[1,0,0] neg_lo:[1,0,0] neg_hi:[1,0,0]
	ds_read_b128 v[84:87], v240 offset:12512
	ds_read_b64 v[100:101], v242 offset:47328
	ds_read_b128 v[92:95], v240 offset:29920
	ds_read_b128 v[80:83], v240 offset:3808
	ds_read_b128 v[88:91], v240 offset:21216
	s_waitcnt lgkmcnt(7)
; template <int CTRL> __device__ __forceinline__ float dppf(float x) { return __builtin_bit_cast(float, __builtin_amdgcn_update_dpp(0, __builtin_bit_cast(int, x), CTRL, 0xF, 0xF, false)); }
; __device__ __forceinline__ void phase_rwkv_scan(const Fr& F, int jr) {
;     ...
;                     for (int pi = 0; pi < 16; ++pi) {
;                         const int p = pg + pi, pn = p < 63 ? p + 1 : 63;
;                         const f32x4 w4n = PW[pn * 16], k4n = PW[1024 + pn * 16], b4n = PW[2048 + pn * 16], d4n = PW[3072 + pn * 16], r4n = PR[pn * 16];
;                         const float vvn = PV[pn * 32];
;                         f32x2 t = S01 * k4.xy; t = S23 * k4.zw + t; float sa = t.x + t.y;
;                         sa += dppf<0x128>(sa);
;                         const f32x2 dv01 = d4.xy * vv, dv23 = d4.zw * vv;
;                         sa += dppf<0x124>(sa);
;                         const f32x2 e01 = S01 * w4.xy + dv01;
;                         sa += dppf<0x122>(sa);
;                         const f32x2 e23 = S23 * w4.zw + dv23;
;                         sa += dppf<0x121>(sa);
;                         S01 = e01 - b4.xy * sa; S23 = e23 - b4.zw * sa;
;                         f32x2 u = S01 * r4.xy; u = S23 * r4.zw + u;
;                         PY[pi * 64] = u.x + u.y;
;                         w4 = w4n; k4 = k4n; b4 = b4n; d4 = d4n; r4 = r4n; vv = vvn;
	v_pk_mul_f32 v[226:227], v[206:207], v[106:107] op_sel_hi:[1,0]
	v_pk_mul_f32 v[228:229], v[206:207], v[96:97] op_sel_hi:[1,0]
	v_pk_fma_f32 v[226:227], v[208:209], v[106:107], v[226:227] op_sel:[0,1,0]
	v_pk_fma_f32 v[228:229], v[208:209], v[96:97], v[228:229] op_sel:[0,1,0]
	v_pk_fma_f32 v[226:227], v[210:211], v[108:109], v[226:227] op_sel_hi:[1,0,1]
	v_pk_fma_f32 v[228:229], v[210:211], v[98:99], v[228:229] op_sel_hi:[1,0,1]
	v_pk_fma_f32 v[226:227], v[212:213], v[108:109], v[226:227] op_sel:[0,1,0]
	v_pk_fma_f32 v[228:229], v[212:213], v[98:99], v[228:229] op_sel:[0,1,0]
	v_pk_mul_f32 v[232:233], v[118:119], v[114:115] op_sel_hi:[1,0]
	v_add_f32_dpp v230, v227, v226 row_ror:8 row_mask:0xf bank_mask:0xf
	v_pk_mul_f32 v[234:235], v[118:119], v[114:115] op_sel:[0,1]
	v_pk_mul_f32 v[236:237], v[118:119], v[116:117] op_sel_hi:[1,0]
	v_add_f32_dpp v230, v230, v230 quad_perm:[1,0,3,2] row_mask:0xf bank_mask:0xf
	v_pk_mul_f32 v[238:239], v[118:119], v[116:117] op_sel:[0,1]
	ds_read_b128 v[96:99], v240 offset:38624
	v_add_f32_dpp v230, v230, v230 quad_perm:[2,3,0,1] row_mask:0xf bank_mask:0xf
	v_pk_fma_f32 v[232:233], v[206:207], v[102:103], v[232:233] op_sel_hi:[1,0,1]
	v_pk_fma_f32 v[234:235], v[208:209], v[102:103], v[234:235] op_sel:[0,1,0]
	v_add_f32_dpp v230, v230, v230 row_half_mirror row_mask:0xf bank_mask:0xf
	v_pk_fma_f32 v[236:237], v[210:211], v[104:105], v[236:237] op_sel_hi:[1,0,1]
	v_pk_fma_f32 v[238:239], v[212:213], v[104:105], v[238:239] op_sel:[0,1,0]
	v_mov_b32_dpp v231, v230 row_ror:8 row_mask:0xf bank_mask:0xf
	ds_write_b64 v217, v[228:229] offset:6912
	v_pk_fma_f32 v[206:207], v[110:111], v[230:231], v[232:233] op_sel_hi:[0,1,1] neg_lo:[1,0,0] neg_hi:[1,0,0]
	v_pk_fma_f32 v[208:209], v[110:111], v[230:231], v[234:235] op_sel:[1,0,0] neg_lo:[1,0,0] neg_hi:[1,0,0]
	v_pk_fma_f32 v[210:211], v[112:113], v[230:231], v[236:237] op_sel_hi:[0,1,1] neg_lo:[1,0,0] neg_hi:[1,0,0]
	v_pk_fma_f32 v[212:213], v[112:113], v[230:231], v[238:239] op_sel:[1,0,0] neg_lo:[1,0,0] neg_hi:[1,0,0]
	ds_read_b128 v[106:109], v240 offset:12784
	ds_read_b64 v[118:119], v242 offset:47600
	ds_read_b128 v[114:117], v240 offset:30192
	ds_read_b128 v[102:105], v240 offset:4080
	ds_read_b128 v[110:113], v240 offset:21488
	s_waitcnt lgkmcnt(7)
	v_pk_mul_f32 v[226:227], v[206:207], v[84:85] op_sel_hi:[1,0]
	v_pk_mul_f32 v[228:229], v[206:207], v[222:223] op_sel_hi:[1,0]
	v_pk_fma_f32 v[226:227], v[208:209], v[84:85], v[226:227] op_sel:[0,1,0]
	v_pk_fma_f32 v[228:229], v[208:209], v[222:223], v[228:229] op_sel:[0,1,0]
	v_pk_fma_f32 v[226:227], v[210:211], v[86:87], v[226:227] op_sel_hi:[1,0,1]
	v_pk_fma_f32 v[228:229], v[210:211], v[224:225], v[228:229] op_sel_hi:[1,0,1]
	v_pk_fma_f32 v[226:227], v[212:213], v[86:87], v[226:227] op_sel:[0,1,0]
	v_pk_fma_f32 v[228:229], v[212:213], v[224:225], v[228:229] op_sel:[0,1,0]
	v_pk_mul_f32 v[232:233], v[100:101], v[92:93] op_sel_hi:[1,0]
	v_add_f32_dpp v230, v227, v226 row_ror:8 row_mask:0xf bank_mask:0xf
	v_pk_mul_f32 v[234:235], v[100:101], v[92:93] op_sel:[0,1]
	v_pk_mul_f32 v[236:237], v[100:101], v[94:95] op_sel_hi:[1,0]
	v_add_f32_dpp v230, v230, v230 quad_perm:[1,0,3,2] row_mask:0xf bank_mask:0xf
	v_pk_mul_f32 v[238:239], v[100:101], v[94:95] op_sel:[0,1]
	ds_read_b128 v[222:225], v240 offset:38896
	v_add_f32_dpp v230, v230, v230 quad_perm:[2,3,0,1] row_mask:0xf bank_mask:0xf
	v_pk_fma_f32 v[232:233], v[206:207], v[80:81], v[232:233] op_sel_hi:[1,0,1]
	v_pk_fma_f32 v[234:235], v[208:209], v[80:81], v[234:235] op_sel:[0,1,0]
	v_add_f32_dpp v230, v230, v230 row_half_mirror row_mask:0xf bank_mask:0xf
	v_pk_fma_f32 v[236:237], v[210:211], v[82:83], v[236:237] op_sel_hi:[1,0,1]
	v_pk_fma_f32 v[238:239], v[212:213], v[82:83], v[238:239] op_sel:[0,1,0]
	v_mov_b32_dpp v231, v230 row_ror:8 row_mask:0xf bank_mask:0xf
	ds_write_b64 v217, v[228:229] offset:7488
	v_pk_fma_f32 v[206:207], v[88:89], v[230:231], v[232:233] op_sel_hi:[0,1,1] neg_lo:[1,0,0] neg_hi:[1,0,0]
	v_pk_fma_f32 v[208:209], v[88:89], v[230:231], v[234:235] op_sel:[1,0,0] neg_lo:[1,0,0] neg_hi:[1,0,0]
	v_pk_fma_f32 v[210:211], v[90:91], v[230:231], v[236:237] op_sel_hi:[0,1,1] neg_lo:[1,0,0] neg_hi:[1,0,0]
	v_pk_fma_f32 v[212:213], v[90:91], v[230:231], v[238:239] op_sel:[1,0,0] neg_lo:[1,0,0] neg_hi:[1,0,0]
	ds_read_b128 v[84:87], v240 offset:13056
	ds_read_b64 v[100:101], v242 offset:47872
	ds_read_b128 v[92:95], v240 offset:30464
	ds_read_b128 v[80:83], v240 offset:4352
	ds_read_b128 v[88:91], v240 offset:21760
	s_waitcnt lgkmcnt(7)
; __device__ __forceinline__ unsigned f2bf(float f) { unsigned u = __builtin_bit_cast(unsigned, f); return (u + 0x7fffu + ((u >> 16) & 1u)) >> 16; }
; template <int CTRL> __device__ __forceinline__ float dppf(float x) { return __builtin_bit_cast(float, __builtin_amdgcn_update_dpp(0, __builtin_bit_cast(int, x), CTRL, 0xF, 0xF, false)); }
; __device__ __forceinline__ void phase_rwkv_scan(const Fr& F, int jr) {
;     ...
;                 for (int pg = 0; pg < 64; pg += 16) {
; #pragma unroll
;                     for (int pi = 0; pi < 16; ++pi) {
;                         const int p = pg + pi, pn = p < 63 ? p + 1 : 63;
;                         const f32x4 w4n = PW[pn * 16], k4n = PW[1024 + pn * 16], b4n = PW[2048 + pn * 16], d4n = PW[3072 + pn * 16], r4n = PR[pn * 16];
;                         const float vvn = PV[pn * 32];
;                         f32x2 t = S01 * k4.xy; t = S23 * k4.zw + t; float sa = t.x + t.y;
;                         sa += dppf<0x128>(sa);
;                         const f32x2 dv01 = d4.xy * vv, dv23 = d4.zw * vv;
;                         sa += dppf<0x124>(sa);
;                         const f32x2 e01 = S01 * w4.xy + dv01;
;                         sa += dppf<0x122>(sa);
;                         const f32x2 e23 = S23 * w4.zw + dv23;
;                         sa += dppf<0x121>(sa);
;                         S01 = e01 - b4.xy * sa; S23 = e23 - b4.zw * sa;
;                         f32x2 u = S01 * r4.xy; u = S23 * r4.zw + u;
;                         PY[pi * 64] = u.x + u.y;
;                         w4 = w4n; k4 = k4n; b4 = b4n; d4 = d4n; r4 = r4n; vv = vvn;
;                     }
;                     asm volatile("s_waitcnt lgkmcnt(0)" ::: "memory");
;                     {
;                         const int j = lane >> 2, q = lane & 3; const float* yp = Ypw + j * 64 + q * 16;
;                         const f32x4 a0 = *(const f32x4*)yp, a1 = *(const f32x4*)(yp + 4), a2 = *(const f32x4*)(yp + 8), a3 = *(const f32x4*)(yp + 12);
;                         const f32x4 ssum = (a0 + a1) + (a2 + a3); const float yv = (ssum.x + ssum.y) + (ssum.z + ssum.w);
;                         const size_t row = (size_t)b * TB + tokof(s, chunk * 64 + pg + j);
;                         Yb[row * D + h * 64 + 32 * half + 4 * wave + q] = (bf16)f2bf(yv);
	v_pk_mul_f32 v[226:227], v[206:207], v[106:107] op_sel_hi:[1,0]
	v_pk_mul_f32 v[228:229], v[206:207], v[96:97] op_sel_hi:[1,0]
	v_pk_fma_f32 v[226:227], v[208:209], v[106:107], v[226:227] op_sel:[0,1,0]
	v_pk_fma_f32 v[228:229], v[208:209], v[96:97], v[228:229] op_sel:[0,1,0]
	v_pk_fma_f32 v[226:227], v[210:211], v[108:109], v[226:227] op_sel_hi:[1,0,1]
	v_pk_fma_f32 v[228:229], v[210:211], v[98:99], v[228:229] op_sel_hi:[1,0,1]
	v_pk_fma_f32 v[226:227], v[212:213], v[108:109], v[226:227] op_sel:[0,1,0]
	v_pk_fma_f32 v[228:229], v[212:213], v[98:99], v[228:229] op_sel:[0,1,0]
	v_pk_mul_f32 v[232:233], v[118:119], v[114:115] op_sel_hi:[1,0]
	v_add_f32_dpp v230, v227, v226 row_ror:8 row_mask:0xf bank_mask:0xf
	v_pk_mul_f32 v[234:235], v[118:119], v[114:115] op_sel:[0,1]
	v_pk_mul_f32 v[236:237], v[118:119], v[116:117] op_sel_hi:[1,0]
	v_add_f32_dpp v230, v230, v230 quad_perm:[1,0,3,2] row_mask:0xf bank_mask:0xf
	v_pk_mul_f32 v[238:239], v[118:119], v[116:117] op_sel:[0,1]
	ds_read_b128 v[96:99], v240 offset:39168
	v_add_f32_dpp v230, v230, v230 quad_perm:[2,3,0,1] row_mask:0xf bank_mask:0xf
	v_pk_fma_f32 v[232:233], v[206:207], v[102:103], v[232:233] op_sel_hi:[1,0,1]
	v_pk_fma_f32 v[234:235], v[208:209], v[102:103], v[234:235] op_sel:[0,1,0]
	v_add_f32_dpp v230, v230, v230 row_half_mirror row_mask:0xf bank_mask:0xf
	v_pk_fma_f32 v[236:237], v[210:211], v[104:105], v[236:237] op_sel_hi:[1,0,1]
	v_pk_fma_f32 v[238:239], v[212:213], v[104:105], v[238:239] op_sel:[0,1,0]
	v_mov_b32_dpp v231, v230 row_ror:8 row_mask:0xf bank_mask:0xf
	ds_write_b64 v217, v[228:229] offset:8064
	v_pk_fma_f32 v[206:207], v[110:111], v[230:231], v[232:233] op_sel_hi:[0,1,1] neg_lo:[1,0,0] neg_hi:[1,0,0]
	v_pk_fma_f32 v[208:209], v[110:111], v[230:231], v[234:235] op_sel:[1,0,0] neg_lo:[1,0,0] neg_hi:[1,0,0]
	v_pk_fma_f32 v[210:211], v[112:113], v[230:231], v[236:237] op_sel_hi:[0,1,1] neg_lo:[1,0,0] neg_hi:[1,0,0]
	v_pk_fma_f32 v[212:213], v[112:113], v[230:231], v[238:239] op_sel:[1,0,0] neg_lo:[1,0,0] neg_hi:[1,0,0]
	ds_read_b128 v[106:109], v240 offset:13328
	ds_read_b64 v[118:119], v242 offset:48144
	ds_read_b128 v[114:117], v240 offset:30736
	ds_read_b128 v[102:105], v240 offset:4624
	ds_read_b128 v[110:113], v240 offset:22032
	s_waitcnt lgkmcnt(7)
	v_pk_mul_f32 v[226:227], v[206:207], v[84:85] op_sel_hi:[1,0]
	v_pk_mul_f32 v[228:229], v[206:207], v[222:223] op_sel_hi:[1,0]
	v_pk_fma_f32 v[226:227], v[208:209], v[84:85], v[226:227] op_sel:[0,1,0]
	v_pk_fma_f32 v[228:229], v[208:209], v[222:223], v[228:229] op_sel:[0,1,0]
	v_pk_fma_f32 v[226:227], v[210:211], v[86:87], v[226:227] op_sel_hi:[1,0,1]
	v_pk_fma_f32 v[228:229], v[210:211], v[224:225], v[228:229] op_sel_hi:[1,0,1]
	v_pk_fma_f32 v[226:227], v[212:213], v[86:87], v[226:227] op_sel:[0,1,0]
	v_pk_fma_f32 v[228:229], v[212:213], v[224:225], v[228:229] op_sel:[0,1,0]
	v_pk_mul_f32 v[232:233], v[100:101], v[92:93] op_sel_hi:[1,0]
	v_add_f32_dpp v230, v227, v226 row_ror:8 row_mask:0xf bank_mask:0xf
	v_pk_mul_f32 v[234:235], v[100:101], v[92:93] op_sel:[0,1]
	v_pk_mul_f32 v[236:237], v[100:101], v[94:95] op_sel_hi:[1,0]
	v_add_f32_dpp v230, v230, v230 quad_perm:[1,0,3,2] row_mask:0xf bank_mask:0xf
	v_pk_mul_f32 v[238:239], v[100:101], v[94:95] op_sel:[0,1]
	ds_read_b128 v[222:225], v240 offset:39440
	v_add_f32_dpp v230, v230, v230 quad_perm:[2,3,0,1] row_mask:0xf bank_mask:0xf
	v_pk_fma_f32 v[232:233], v[206:207], v[80:81], v[232:233] op_sel_hi:[1,0,1]
	v_pk_fma_f32 v[234:235], v[208:209], v[80:81], v[234:235] op_sel:[0,1,0]
	v_add_f32_dpp v230, v230, v230 row_half_mirror row_mask:0xf bank_mask:0xf
	v_pk_fma_f32 v[236:237], v[210:211], v[82:83], v[236:237] op_sel_hi:[1,0,1]
	v_pk_fma_f32 v[238:239], v[212:213], v[82:83], v[238:239] op_sel:[0,1,0]
	v_mov_b32_dpp v231, v230 row_ror:8 row_mask:0xf bank_mask:0xf
	ds_write_b64 v217, v[228:229] offset:8640
	v_pk_fma_f32 v[206:207], v[88:89], v[230:231], v[232:233] op_sel_hi:[0,1,1] neg_lo:[1,0,0] neg_hi:[1,0,0]
	v_pk_fma_f32 v[208:209], v[88:89], v[230:231], v[234:235] op_sel:[1,0,0] neg_lo:[1,0,0] neg_hi:[1,0,0]
	v_pk_fma_f32 v[210:211], v[90:91], v[230:231], v[236:237] op_sel_hi:[0,1,1] neg_lo:[1,0,0] neg_hi:[1,0,0]
	v_pk_fma_f32 v[212:213], v[90:91], v[230:231], v[238:239] op_sel:[1,0,0] neg_lo:[1,0,0] neg_hi:[1,0,0]
	s_mov_b32 s87, s15
	s_add_i32 s15, s15, s19
	s_waitcnt lgkmcnt(2)
	ds_read_b128 v[84:87], v240 offset:13600
	ds_read_b64 v[100:101], v242 offset:48416
	ds_read_b128 v[92:95], v240 offset:31008
	ds_read_b128 v[80:83], v240 offset:4896
	ds_read_b128 v[88:91], v240 offset:22304
	ds_read_b128 v[0:3], v218 offset:0
	ds_read_b128 v[4:7], v218 offset:16
	ds_read_b128 v[8:11], v218 offset:32
	ds_read_b128 v[12:15], v218 offset:48
	v_pk_mul_f32 v[226:227], v[206:207], v[106:107] op_sel_hi:[1,0]
	v_pk_mul_f32 v[32:33], v[206:207], v[96:97] op_sel_hi:[1,0]
	v_pk_fma_f32 v[226:227], v[208:209], v[106:107], v[226:227] op_sel:[0,1,0]
	v_pk_fma_f32 v[32:33], v[208:209], v[96:97], v[32:33] op_sel:[0,1,0]
	v_pk_fma_f32 v[226:227], v[210:211], v[108:109], v[226:227] op_sel_hi:[1,0,1]
	v_pk_fma_f32 v[32:33], v[210:211], v[98:99], v[32:33] op_sel_hi:[1,0,1]
	v_pk_fma_f32 v[226:227], v[212:213], v[108:109], v[226:227] op_sel:[0,1,0]
	v_pk_fma_f32 v[32:33], v[212:213], v[98:99], v[32:33] op_sel:[0,1,0]
	v_pk_mul_f32 v[232:233], v[118:119], v[114:115] op_sel_hi:[1,0]
	v_add_f32_dpp v230, v227, v226 row_ror:8 row_mask:0xf bank_mask:0xf
	v_pk_mul_f32 v[234:235], v[118:119], v[114:115] op_sel:[0,1]
	v_pk_mul_f32 v[236:237], v[118:119], v[116:117] op_sel_hi:[1,0]
	v_add_f32_dpp v230, v230, v230 quad_perm:[1,0,3,2] row_mask:0xf bank_mask:0xf
	v_pk_mul_f32 v[238:239], v[118:119], v[116:117] op_sel:[0,1]
	ds_read_b128 v[96:99], v240 offset:39712
	v_add_f32_dpp v230, v230, v230 quad_perm:[2,3,0,1] row_mask:0xf bank_mask:0xf
	v_pk_fma_f32 v[232:233], v[206:207], v[102:103], v[232:233] op_sel_hi:[1,0,1]
	v_pk_fma_f32 v[234:235], v[208:209], v[102:103], v[234:235] op_sel:[0,1,0]
	v_add_f32_dpp v230, v230, v230 row_half_mirror row_mask:0xf bank_mask:0xf
	v_pk_fma_f32 v[236:237], v[210:211], v[104:105], v[236:237] op_sel_hi:[1,0,1]
	v_pk_fma_f32 v[238:239], v[212:213], v[104:105], v[238:239] op_sel:[0,1,0]
	v_mov_b32_dpp v231, v230 row_ror:8 row_mask:0xf bank_mask:0xf
	v_pk_fma_f32 v[206:207], v[110:111], v[230:231], v[232:233] op_sel_hi:[0,1,1] neg_lo:[1,0,0] neg_hi:[1,0,0]
	v_pk_fma_f32 v[208:209], v[110:111], v[230:231], v[234:235] op_sel:[1,0,0] neg_lo:[1,0,0] neg_hi:[1,0,0]
	v_pk_fma_f32 v[210:211], v[112:113], v[230:231], v[236:237] op_sel_hi:[0,1,1] neg_lo:[1,0,0] neg_hi:[1,0,0]
	v_pk_fma_f32 v[212:213], v[112:113], v[230:231], v[238:239] op_sel:[1,0,0] neg_lo:[1,0,0] neg_hi:[1,0,0]
	s_waitcnt lgkmcnt(5)
; template <int CTRL> __device__ __forceinline__ float dppf(float x) { return __builtin_bit_cast(float, __builtin_amdgcn_update_dpp(0, __builtin_bit_cast(int, x), CTRL, 0xF, 0xF, false)); }
; __device__ __forceinline__ void phase_rwkv_scan(const Fr& F, int jr) {
;     ...
;                 for (int pg = 0; pg < 64; pg += 16) {
; #pragma unroll
;                     for (int pi = 0; pi < 16; ++pi) {
;                         const int p = pg + pi, pn = p < 63 ? p + 1 : 63;
;                         const f32x4 w4n = PW[pn * 16], k4n = PW[1024 + pn * 16], b4n = PW[2048 + pn * 16], d4n = PW[3072 + pn * 16], r4n = PR[pn * 16];
;                         const float vvn = PV[pn * 32];
;                         f32x2 t = S01 * k4.xy; t = S23 * k4.zw + t; float sa = t.x + t.y;
;                         sa += dppf<0x128>(sa);
;                         const f32x2 dv01 = d4.xy * vv, dv23 = d4.zw * vv;
;                         sa += dppf<0x124>(sa);
;                         const f32x2 e01 = S01 * w4.xy + dv01;
;                         sa += dppf<0x122>(sa);
;                         const f32x2 e23 = S23 * w4.zw + dv23;
;                         sa += dppf<0x121>(sa);
;                         S01 = e01 - b4.xy * sa; S23 = e23 - b4.zw * sa;
;                         f32x2 u = S01 * r4.xy; u = S23 * r4.zw + u;
;                         PY[pi * 64] = u.x + u.y;
;                         w4 = w4n; k4 = k4n; b4 = b4n; d4 = d4n; r4 = r4n; vv = vvn;
;                     }
;                     asm volatile("s_waitcnt lgkmcnt(0)" ::: "memory");
;                     {
;                         const int j = lane >> 2, q = lane & 3; const float* yp = Ypw + j * 64 + q * 16;
;                         const f32x4 a0 = *(const f32x4*)yp, a1 = *(const f32x4*)(yp + 4), a2 = *(const f32x4*)(yp + 8), a3 = *(const f32x4*)(yp + 12);
;                         const f32x4 ssum = (a0 + a1) + (a2 + a3); const float yv = (ssum.x + ssum.y) + (ssum.z + ssum.w);
	ds_read_b128 v[106:109], v240 offset:13872
	ds_read_b64 v[118:119], v242 offset:48688
	ds_read_b128 v[114:117], v240 offset:31280
	ds_read_b128 v[102:105], v240 offset:5168
	ds_read_b128 v[110:113], v240 offset:22576
	ds_read_b128 v[16:19], v218 offset:64
	ds_read_b128 v[20:23], v218 offset:80
	ds_read_b128 v[24:27], v218 offset:96
	ds_read_b128 v[28:31], v218 offset:112
	ds_write_b64 v217, v[32:33] offset:0
	v_pk_mul_f32 v[226:227], v[206:207], v[84:85] op_sel_hi:[1,0]
	v_pk_mul_f32 v[228:229], v[206:207], v[222:223] op_sel_hi:[1,0]
	v_pk_fma_f32 v[226:227], v[208:209], v[84:85], v[226:227] op_sel:[0,1,0]
	v_pk_fma_f32 v[228:229], v[208:209], v[222:223], v[228:229] op_sel:[0,1,0]
	v_pk_fma_f32 v[226:227], v[210:211], v[86:87], v[226:227] op_sel_hi:[1,0,1]
	v_pk_fma_f32 v[228:229], v[210:211], v[224:225], v[228:229] op_sel_hi:[1,0,1]
	v_pk_fma_f32 v[226:227], v[212:213], v[86:87], v[226:227] op_sel:[0,1,0]
	v_pk_fma_f32 v[228:229], v[212:213], v[224:225], v[228:229] op_sel:[0,1,0]
	v_pk_mul_f32 v[232:233], v[100:101], v[92:93] op_sel_hi:[1,0]
	v_add_f32_dpp v230, v227, v226 row_ror:8 row_mask:0xf bank_mask:0xf
	v_pk_mul_f32 v[234:235], v[100:101], v[92:93] op_sel:[0,1]
	v_pk_mul_f32 v[236:237], v[100:101], v[94:95] op_sel_hi:[1,0]
	v_add_f32_dpp v230, v230, v230 quad_perm:[1,0,3,2] row_mask:0xf bank_mask:0xf
	v_pk_mul_f32 v[238:239], v[100:101], v[94:95] op_sel:[0,1]
	s_waitcnt lgkmcnt(11)
	ds_read_b128 v[222:225], v240 offset:39984
	v_add_f32_dpp v230, v230, v230 quad_perm:[2,3,0,1] row_mask:0xf bank_mask:0xf
	v_pk_fma_f32 v[232:233], v[206:207], v[80:81], v[232:233] op_sel_hi:[1,0,1]
	v_pk_fma_f32 v[234:235], v[208:209], v[80:81], v[234:235] op_sel:[0,1,0]
	v_add_f32_dpp v230, v230, v230 row_half_mirror row_mask:0xf bank_mask:0xf
	v_pk_fma_f32 v[236:237], v[210:211], v[82:83], v[236:237] op_sel_hi:[1,0,1]
	v_pk_fma_f32 v[238:239], v[212:213], v[82:83], v[238:239] op_sel:[0,1,0]
	v_mov_b32_dpp v231, v230 row_ror:8 row_mask:0xf bank_mask:0xf
	ds_write_b64 v217, v[228:229] offset:576
	v_pk_fma_f32 v[206:207], v[88:89], v[230:231], v[232:233] op_sel_hi:[0,1,1] neg_lo:[1,0,0] neg_hi:[1,0,0]
	v_pk_fma_f32 v[208:209], v[88:89], v[230:231], v[234:235] op_sel:[1,0,0] neg_lo:[1,0,0] neg_hi:[1,0,0]
	v_pk_fma_f32 v[210:211], v[90:91], v[230:231], v[236:237] op_sel_hi:[0,1,1] neg_lo:[1,0,0] neg_hi:[1,0,0]
	v_pk_fma_f32 v[212:213], v[90:91], v[230:231], v[238:239] op_sel:[1,0,0] neg_lo:[1,0,0] neg_hi:[1,0,0]
	s_waitcnt lgkmcnt(7)
	ds_read_b128 v[84:87], v240 offset:14144
	ds_read_b64 v[100:101], v242 offset:48960
	ds_read_b128 v[92:95], v240 offset:31552
	ds_read_b128 v[80:83], v240 offset:5440
	ds_read_b128 v[88:91], v240 offset:22848
	v_pk_mul_f32 v[226:227], v[206:207], v[106:107] op_sel_hi:[1,0]
	v_pk_mul_f32 v[228:229], v[206:207], v[96:97] op_sel_hi:[1,0]
	v_pk_fma_f32 v[226:227], v[208:209], v[106:107], v[226:227] op_sel:[0,1,0]
	v_pk_fma_f32 v[228:229], v[208:209], v[96:97], v[228:229] op_sel:[0,1,0]
	v_pk_fma_f32 v[226:227], v[210:211], v[108:109], v[226:227] op_sel_hi:[1,0,1]
	v_pk_fma_f32 v[228:229], v[210:211], v[98:99], v[228:229] op_sel_hi:[1,0,1]
	v_pk_fma_f32 v[226:227], v[212:213], v[108:109], v[226:227] op_sel:[0,1,0]
	v_pk_fma_f32 v[228:229], v[212:213], v[98:99], v[228:229] op_sel:[0,1,0]
	v_pk_add_f32 v[0:1], v[0:1], v[2:3]
	v_pk_mul_f32 v[232:233], v[118:119], v[114:115] op_sel_hi:[1,0]
	v_add_f32_dpp v230, v227, v226 row_ror:8 row_mask:0xf bank_mask:0xf
	v_pk_add_f32 v[4:5], v[4:5], v[6:7]
	v_pk_mul_f32 v[234:235], v[118:119], v[114:115] op_sel:[0,1]
	v_pk_mul_f32 v[236:237], v[118:119], v[116:117] op_sel_hi:[1,0]
	v_add_f32_dpp v230, v230, v230 quad_perm:[1,0,3,2] row_mask:0xf bank_mask:0xf
	v_pk_add_f32 v[8:9], v[8:9], v[10:11]
	v_pk_mul_f32 v[238:239], v[118:119], v[116:117] op_sel:[0,1]
	ds_read_b128 v[96:99], v240 offset:40256
	v_add_f32_dpp v230, v230, v230 quad_perm:[2,3,0,1] row_mask:0xf bank_mask:0xf
	v_pk_add_f32 v[12:13], v[12:13], v[14:15]
	v_pk_fma_f32 v[232:233], v[206:207], v[102:103], v[232:233] op_sel_hi:[1,0,1]
	v_pk_fma_f32 v[234:235], v[208:209], v[102:103], v[234:235] op_sel:[0,1,0]
	v_add_f32_dpp v230, v230, v230 row_half_mirror row_mask:0xf bank_mask:0xf
	v_pk_add_f32 v[0:1], v[0:1], v[4:5]
	v_pk_fma_f32 v[236:237], v[210:211], v[104:105], v[236:237] op_sel_hi:[1,0,1]
	v_pk_fma_f32 v[238:239], v[212:213], v[104:105], v[238:239] op_sel:[0,1,0]
	v_mov_b32_dpp v231, v230 row_ror:8 row_mask:0xf bank_mask:0xf
	s_waitcnt lgkmcnt(11)
	v_pk_add_f32 v[16:17], v[16:17], v[18:19]
	ds_write_b64 v217, v[228:229] offset:1152
	v_pk_fma_f32 v[206:207], v[110:111], v[230:231], v[232:233] op_sel_hi:[0,1,1] neg_lo:[1,0,0] neg_hi:[1,0,0]
	v_pk_fma_f32 v[208:209], v[110:111], v[230:231], v[234:235] op_sel:[1,0,0] neg_lo:[1,0,0] neg_hi:[1,0,0]
	v_pk_add_f32 v[20:21], v[20:21], v[22:23]
	v_pk_fma_f32 v[210:211], v[112:113], v[230:231], v[236:237] op_sel_hi:[0,1,1] neg_lo:[1,0,0] neg_hi:[1,0,0]
	v_pk_fma_f32 v[212:213], v[112:113], v[230:231], v[238:239] op_sel:[1,0,0] neg_lo:[1,0,0] neg_hi:[1,0,0]
	v_pk_add_f32 v[8:9], v[8:9], v[12:13]
	s_waitcnt lgkmcnt(2)
; __device__ __forceinline__ unsigned f2bf(float f) { unsigned u = __builtin_bit_cast(unsigned, f); return (u + 0x7fffu + ((u >> 16) & 1u)) >> 16; }
; template <int CTRL> __device__ __forceinline__ float dppf(float x) { return __builtin_bit_cast(float, __builtin_amdgcn_update_dpp(0, __builtin_bit_cast(int, x), CTRL, 0xF, 0xF, false)); }
; __device__ __forceinline__ void phase_rwkv_scan(const Fr& F, int jr) {
;     ...
;                 for (int pg = 0; pg < 64; pg += 16) {
; #pragma unroll
;                     for (int pi = 0; pi < 16; ++pi) {
;                         const int p = pg + pi, pn = p < 63 ? p + 1 : 63;
;                         const f32x4 w4n = PW[pn * 16], k4n = PW[1024 + pn * 16], b4n = PW[2048 + pn * 16], d4n = PW[3072 + pn * 16], r4n = PR[pn * 16];
;                         const float vvn = PV[pn * 32];
;                         f32x2 t = S01 * k4.xy; t = S23 * k4.zw + t; float sa = t.x + t.y;
;                         sa += dppf<0x128>(sa);
;                         const f32x2 dv01 = d4.xy * vv, dv23 = d4.zw * vv;
;                         sa += dppf<0x124>(sa);
;                         const f32x2 e01 = S01 * w4.xy + dv01;
;                         sa += dppf<0x122>(sa);
;                         const f32x2 e23 = S23 * w4.zw + dv23;
;                         sa += dppf<0x121>(sa);
;                         S01 = e01 - b4.xy * sa; S23 = e23 - b4.zw * sa;
;                         f32x2 u = S01 * r4.xy; u = S23 * r4.zw + u;
;                         PY[pi * 64] = u.x + u.y;
;                         w4 = w4n; k4 = k4n; b4 = b4n; d4 = d4n; r4 = r4n; vv = vvn;
;                     }
;                     asm volatile("s_waitcnt lgkmcnt(0)" ::: "memory");
;                     {
;                         const int j = lane >> 2, q = lane & 3; const float* yp = Ypw + j * 64 + q * 16;
;                         const f32x4 a0 = *(const f32x4*)yp, a1 = *(const f32x4*)(yp + 4), a2 = *(const f32x4*)(yp + 8), a3 = *(const f32x4*)(yp + 12);
;                         const f32x4 ssum = (a0 + a1) + (a2 + a3); const float yv = (ssum.x + ssum.y) + (ssum.z + ssum.w);
;                         const size_t row = (size_t)b * TB + tokof(s, chunk * 64 + pg + j);
;                         Yb[row * D + h * 64 + 32 * half + 4 * wave + q] = (bf16)f2bf(yv);
	ds_read_b128 v[106:109], v240 offset:14416
	ds_read_b64 v[118:119], v242 offset:49232
	ds_read_b128 v[114:117], v240 offset:31824
	ds_read_b128 v[102:105], v240 offset:5712
	ds_read_b128 v[110:113], v240 offset:23120
	v_pk_mul_f32 v[226:227], v[206:207], v[84:85] op_sel_hi:[1,0]
	v_pk_mul_f32 v[228:229], v[206:207], v[222:223] op_sel_hi:[1,0]
	v_pk_fma_f32 v[226:227], v[208:209], v[84:85], v[226:227] op_sel:[0,1,0]
	v_pk_fma_f32 v[228:229], v[208:209], v[222:223], v[228:229] op_sel:[0,1,0]
	v_pk_fma_f32 v[226:227], v[210:211], v[86:87], v[226:227] op_sel_hi:[1,0,1]
	v_pk_fma_f32 v[228:229], v[210:211], v[224:225], v[228:229] op_sel_hi:[1,0,1]
	v_pk_fma_f32 v[226:227], v[212:213], v[86:87], v[226:227] op_sel:[0,1,0]
	v_pk_fma_f32 v[228:229], v[212:213], v[224:225], v[228:229] op_sel:[0,1,0]
	v_pk_add_f32 v[24:25], v[24:25], v[26:27]
	v_pk_mul_f32 v[232:233], v[100:101], v[92:93] op_sel_hi:[1,0]
	v_add_f32_dpp v230, v227, v226 row_ror:8 row_mask:0xf bank_mask:0xf
	v_pk_add_f32 v[28:29], v[28:29], v[30:31]
	v_pk_mul_f32 v[234:235], v[100:101], v[92:93] op_sel:[0,1]
	v_pk_mul_f32 v[236:237], v[100:101], v[94:95] op_sel_hi:[1,0]
	v_add_f32_dpp v230, v230, v230 quad_perm:[1,0,3,2] row_mask:0xf bank_mask:0xf
	v_pk_add_f32 v[16:17], v[16:17], v[20:21]
	v_pk_mul_f32 v[238:239], v[100:101], v[94:95] op_sel:[0,1]
	ds_read_b128 v[222:225], v240 offset:40528
	v_add_f32_dpp v230, v230, v230 quad_perm:[2,3,0,1] row_mask:0xf bank_mask:0xf
	v_pk_add_f32 v[0:1], v[0:1], v[8:9]
	v_pk_fma_f32 v[232:233], v[206:207], v[80:81], v[232:233] op_sel_hi:[1,0,1]
	v_pk_fma_f32 v[234:235], v[208:209], v[80:81], v[234:235] op_sel:[0,1,0]
	v_add_f32_dpp v230, v230, v230 row_half_mirror row_mask:0xf bank_mask:0xf
	v_pk_add_f32 v[24:25], v[24:25], v[28:29]
	v_pk_fma_f32 v[236:237], v[210:211], v[82:83], v[236:237] op_sel_hi:[1,0,1]
	v_pk_fma_f32 v[238:239], v[212:213], v[82:83], v[238:239] op_sel:[0,1,0]
	v_mov_b32_dpp v231, v230 row_ror:8 row_mask:0xf bank_mask:0xf
	v_add_u32_e32 v243, s87, v219
	ds_write_b64 v217, v[228:229] offset:1728
	v_pk_fma_f32 v[206:207], v[88:89], v[230:231], v[232:233] op_sel_hi:[0,1,1] neg_lo:[1,0,0] neg_hi:[1,0,0]
	v_pk_fma_f32 v[208:209], v[88:89], v[230:231], v[234:235] op_sel:[1,0,0] neg_lo:[1,0,0] neg_hi:[1,0,0]
	v_pk_add_f32 v[16:17], v[16:17], v[24:25]
	v_pk_fma_f32 v[210:211], v[90:91], v[230:231], v[236:237] op_sel_hi:[0,1,1] neg_lo:[1,0,0] neg_hi:[1,0,0]
	v_pk_fma_f32 v[212:213], v[90:91], v[230:231], v[238:239] op_sel:[1,0,0] neg_lo:[1,0,0] neg_hi:[1,0,0]
	v_lshl_add_u32 v243, v243, 11, v220
	s_waitcnt lgkmcnt(2)
	ds_read_b128 v[84:87], v240 offset:14688
	ds_read_b64 v[100:101], v242 offset:49504
	ds_read_b128 v[92:95], v240 offset:32096
	ds_read_b128 v[80:83], v240 offset:5984
	ds_read_b128 v[88:91], v240 offset:23392
	v_pk_mul_f32 v[226:227], v[206:207], v[106:107] op_sel_hi:[1,0]
	v_pk_mul_f32 v[228:229], v[206:207], v[96:97] op_sel_hi:[1,0]
	v_pk_fma_f32 v[226:227], v[208:209], v[106:107], v[226:227] op_sel:[0,1,0]
	v_pk_fma_f32 v[228:229], v[208:209], v[96:97], v[228:229] op_sel:[0,1,0]
	v_pk_fma_f32 v[226:227], v[210:211], v[108:109], v[226:227] op_sel_hi:[1,0,1]
	v_pk_fma_f32 v[228:229], v[210:211], v[98:99], v[228:229] op_sel_hi:[1,0,1]
	v_pk_fma_f32 v[226:227], v[212:213], v[108:109], v[226:227] op_sel:[0,1,0]
	v_pk_fma_f32 v[228:229], v[212:213], v[98:99], v[228:229] op_sel:[0,1,0]
	v_pk_add_f32 v[0:1], v[0:1], v[16:17] op_sel:[0,1] op_sel_hi:[1,0]
	v_pk_mul_f32 v[232:233], v[118:119], v[114:115] op_sel_hi:[1,0]
	v_add_f32_dpp v230, v227, v226 row_ror:8 row_mask:0xf bank_mask:0xf
	s_nop 0
	v_pk_mul_f32 v[234:235], v[118:119], v[114:115] op_sel:[0,1]
	v_pk_mul_f32 v[236:237], v[118:119], v[116:117] op_sel_hi:[1,0]
	v_add_f32_dpp v230, v230, v230 quad_perm:[1,0,3,2] row_mask:0xf bank_mask:0xf
	v_cvt_pk_bf16_f32 v244, v0, v1
	v_pk_mul_f32 v[238:239], v[118:119], v[116:117] op_sel:[0,1]
	ds_read_b128 v[96:99], v240 offset:40800
	v_add_f32_dpp v230, v230, v230 quad_perm:[2,3,0,1] row_mask:0xf bank_mask:0xf
	s_nop 0
	global_store_dword v243, v244, s[20:21]
	v_pk_fma_f32 v[232:233], v[206:207], v[102:103], v[232:233] op_sel_hi:[1,0,1]
	v_pk_fma_f32 v[234:235], v[208:209], v[102:103], v[234:235] op_sel:[0,1,0]
	v_add_f32_dpp v230, v230, v230 row_half_mirror row_mask:0xf bank_mask:0xf
	v_pk_fma_f32 v[236:237], v[210:211], v[104:105], v[236:237] op_sel_hi:[1,0,1]
	v_pk_fma_f32 v[238:239], v[212:213], v[104:105], v[238:239] op_sel:[0,1,0]
	v_mov_b32_dpp v231, v230 row_ror:8 row_mask:0xf bank_mask:0xf
	ds_write_b64 v217, v[228:229] offset:2304
	v_pk_fma_f32 v[206:207], v[110:111], v[230:231], v[232:233] op_sel_hi:[0,1,1] neg_lo:[1,0,0] neg_hi:[1,0,0]
	v_pk_fma_f32 v[208:209], v[110:111], v[230:231], v[234:235] op_sel:[1,0,0] neg_lo:[1,0,0] neg_hi:[1,0,0]
	v_pk_fma_f32 v[210:211], v[112:113], v[230:231], v[236:237] op_sel_hi:[0,1,1] neg_lo:[1,0,0] neg_hi:[1,0,0]
	v_pk_fma_f32 v[212:213], v[112:113], v[230:231], v[238:239] op_sel:[1,0,0] neg_lo:[1,0,0] neg_hi:[1,0,0]
	ds_read_b128 v[106:109], v240 offset:14960
	ds_read_b64 v[118:119], v242 offset:49776
	ds_read_b128 v[114:117], v240 offset:32368
	ds_read_b128 v[102:105], v240 offset:6256
	ds_read_b128 v[110:113], v240 offset:23664
	s_waitcnt lgkmcnt(7)
; template <int CTRL> __device__ __forceinline__ float dppf(float x) { return __builtin_bit_cast(float, __builtin_amdgcn_update_dpp(0, __builtin_bit_cast(int, x), CTRL, 0xF, 0xF, false)); }
; __device__ __forceinline__ void phase_rwkv_scan(const Fr& F, int jr) {
;     ...
;                 for (int pg = 0; pg < 64; pg += 16) {
; #pragma unroll
;                     for (int pi = 0; pi < 16; ++pi) {
;                         const int p = pg + pi, pn = p < 63 ? p + 1 : 63;
;                         const f32x4 w4n = PW[pn * 16], k4n = PW[1024 + pn * 16], b4n = PW[2048 + pn * 16], d4n = PW[3072 + pn * 16], r4n = PR[pn * 16];
;                         const float vvn = PV[pn * 32];
;                         f32x2 t = S01 * k4.xy; t = S23 * k4.zw + t; float sa = t.x + t.y;
;                         sa += dppf<0x128>(sa);
;                         const f32x2 dv01 = d4.xy * vv, dv23 = d4.zw * vv;
;                         sa += dppf<0x124>(sa);
;                         const f32x2 e01 = S01 * w4.xy + dv01;
;                         sa += dppf<0x122>(sa);
;                         const f32x2 e23 = S23 * w4.zw + dv23;
;                         sa += dppf<0x121>(sa);
;                         S01 = e01 - b4.xy * sa; S23 = e23 - b4.zw * sa;
;                         f32x2 u = S01 * r4.xy; u = S23 * r4.zw + u;
;                         PY[pi * 64] = u.x + u.y;
;                         w4 = w4n; k4 = k4n; b4 = b4n; d4 = d4n; r4 = r4n; vv = vvn;
;                     }
	v_pk_mul_f32 v[226:227], v[206:207], v[84:85] op_sel_hi:[1,0]
	v_pk_mul_f32 v[228:229], v[206:207], v[222:223] op_sel_hi:[1,0]
	v_pk_fma_f32 v[226:227], v[208:209], v[84:85], v[226:227] op_sel:[0,1,0]
	v_pk_fma_f32 v[228:229], v[208:209], v[222:223], v[228:229] op_sel:[0,1,0]
	v_pk_fma_f32 v[226:227], v[210:211], v[86:87], v[226:227] op_sel_hi:[1,0,1]
	v_pk_fma_f32 v[228:229], v[210:211], v[224:225], v[228:229] op_sel_hi:[1,0,1]
	v_pk_fma_f32 v[226:227], v[212:213], v[86:87], v[226:227] op_sel:[0,1,0]
	v_pk_fma_f32 v[228:229], v[212:213], v[224:225], v[228:229] op_sel:[0,1,0]
	v_pk_mul_f32 v[232:233], v[100:101], v[92:93] op_sel_hi:[1,0]
	v_add_f32_dpp v230, v227, v226 row_ror:8 row_mask:0xf bank_mask:0xf
	v_pk_mul_f32 v[234:235], v[100:101], v[92:93] op_sel:[0,1]
	v_pk_mul_f32 v[236:237], v[100:101], v[94:95] op_sel_hi:[1,0]
	v_add_f32_dpp v230, v230, v230 quad_perm:[1,0,3,2] row_mask:0xf bank_mask:0xf
	v_pk_mul_f32 v[238:239], v[100:101], v[94:95] op_sel:[0,1]
	ds_read_b128 v[222:225], v240 offset:41072
	v_add_f32_dpp v230, v230, v230 quad_perm:[2,3,0,1] row_mask:0xf bank_mask:0xf
	v_pk_fma_f32 v[232:233], v[206:207], v[80:81], v[232:233] op_sel_hi:[1,0,1]
	v_pk_fma_f32 v[234:235], v[208:209], v[80:81], v[234:235] op_sel:[0,1,0]
	v_add_f32_dpp v230, v230, v230 row_half_mirror row_mask:0xf bank_mask:0xf
	v_pk_fma_f32 v[236:237], v[210:211], v[82:83], v[236:237] op_sel_hi:[1,0,1]
	v_pk_fma_f32 v[238:239], v[212:213], v[82:83], v[238:239] op_sel:[0,1,0]
	v_mov_b32_dpp v231, v230 row_ror:8 row_mask:0xf bank_mask:0xf
	ds_write_b64 v217, v[228:229] offset:2880
	v_pk_fma_f32 v[206:207], v[88:89], v[230:231], v[232:233] op_sel_hi:[0,1,1] neg_lo:[1,0,0] neg_hi:[1,0,0]
	v_pk_fma_f32 v[208:209], v[88:89], v[230:231], v[234:235] op_sel:[1,0,0] neg_lo:[1,0,0] neg_hi:[1,0,0]
	v_pk_fma_f32 v[210:211], v[90:91], v[230:231], v[236:237] op_sel_hi:[0,1,1] neg_lo:[1,0,0] neg_hi:[1,0,0]
	v_pk_fma_f32 v[212:213], v[90:91], v[230:231], v[238:239] op_sel:[1,0,0] neg_lo:[1,0,0] neg_hi:[1,0,0]
	ds_read_b128 v[84:87], v240 offset:15232
	ds_read_b64 v[100:101], v242 offset:50048
	ds_read_b128 v[92:95], v240 offset:32640
	ds_read_b128 v[80:83], v240 offset:6528
	ds_read_b128 v[88:91], v240 offset:23936
	s_waitcnt lgkmcnt(7)
	v_pk_mul_f32 v[226:227], v[206:207], v[106:107] op_sel_hi:[1,0]
	v_pk_mul_f32 v[228:229], v[206:207], v[96:97] op_sel_hi:[1,0]
	v_pk_fma_f32 v[226:227], v[208:209], v[106:107], v[226:227] op_sel:[0,1,0]
	v_pk_fma_f32 v[228:229], v[208:209], v[96:97], v[228:229] op_sel:[0,1,0]
	v_pk_fma_f32 v[226:227], v[210:211], v[108:109], v[226:227] op_sel_hi:[1,0,1]
	v_pk_fma_f32 v[228:229], v[210:211], v[98:99], v[228:229] op_sel_hi:[1,0,1]
	v_pk_fma_f32 v[226:227], v[212:213], v[108:109], v[226:227] op_sel:[0,1,0]
	v_pk_fma_f32 v[228:229], v[212:213], v[98:99], v[228:229] op_sel:[0,1,0]
	v_pk_mul_f32 v[232:233], v[118:119], v[114:115] op_sel_hi:[1,0]
	v_add_f32_dpp v230, v227, v226 row_ror:8 row_mask:0xf bank_mask:0xf
	v_pk_mul_f32 v[234:235], v[118:119], v[114:115] op_sel:[0,1]
	v_pk_mul_f32 v[236:237], v[118:119], v[116:117] op_sel_hi:[1,0]
	v_add_f32_dpp v230, v230, v230 quad_perm:[1,0,3,2] row_mask:0xf bank_mask:0xf
	v_pk_mul_f32 v[238:239], v[118:119], v[116:117] op_sel:[0,1]
	ds_read_b128 v[96:99], v240 offset:41344
	v_add_f32_dpp v230, v230, v230 quad_perm:[2,3,0,1] row_mask:0xf bank_mask:0xf
	v_pk_fma_f32 v[232:233], v[206:207], v[102:103], v[232:233] op_sel_hi:[1,0,1]
	v_pk_fma_f32 v[234:235], v[208:209], v[102:103], v[234:235] op_sel:[0,1,0]
	v_add_f32_dpp v230, v230, v230 row_half_mirror row_mask:0xf bank_mask:0xf
	v_pk_fma_f32 v[236:237], v[210:211], v[104:105], v[236:237] op_sel_hi:[1,0,1]
	v_pk_fma_f32 v[238:239], v[212:213], v[104:105], v[238:239] op_sel:[0,1,0]
	v_mov_b32_dpp v231, v230 row_ror:8 row_mask:0xf bank_mask:0xf
	ds_write_b64 v217, v[228:229] offset:3456
	v_pk_fma_f32 v[206:207], v[110:111], v[230:231], v[232:233] op_sel_hi:[0,1,1] neg_lo:[1,0,0] neg_hi:[1,0,0]
	v_pk_fma_f32 v[208:209], v[110:111], v[230:231], v[234:235] op_sel:[1,0,0] neg_lo:[1,0,0] neg_hi:[1,0,0]
	v_pk_fma_f32 v[210:211], v[112:113], v[230:231], v[236:237] op_sel_hi:[0,1,1] neg_lo:[1,0,0] neg_hi:[1,0,0]
	v_pk_fma_f32 v[212:213], v[112:113], v[230:231], v[238:239] op_sel:[1,0,0] neg_lo:[1,0,0] neg_hi:[1,0,0]
	ds_read_b128 v[106:109], v240 offset:15504
	ds_read_b64 v[118:119], v242 offset:50320
	ds_read_b128 v[114:117], v240 offset:32912
	ds_read_b128 v[102:105], v240 offset:6800
	ds_read_b128 v[110:113], v240 offset:24208
	s_waitcnt lgkmcnt(7)
	v_pk_mul_f32 v[226:227], v[206:207], v[84:85] op_sel_hi:[1,0]
	v_pk_mul_f32 v[228:229], v[206:207], v[222:223] op_sel_hi:[1,0]
	v_pk_fma_f32 v[226:227], v[208:209], v[84:85], v[226:227] op_sel:[0,1,0]
	v_pk_fma_f32 v[228:229], v[208:209], v[222:223], v[228:229] op_sel:[0,1,0]
	v_pk_fma_f32 v[226:227], v[210:211], v[86:87], v[226:227] op_sel_hi:[1,0,1]
	v_pk_fma_f32 v[228:229], v[210:211], v[224:225], v[228:229] op_sel_hi:[1,0,1]
	v_pk_fma_f32 v[226:227], v[212:213], v[86:87], v[226:227] op_sel:[0,1,0]
	v_pk_fma_f32 v[228:229], v[212:213], v[224:225], v[228:229] op_sel:[0,1,0]
	v_pk_mul_f32 v[232:233], v[100:101], v[92:93] op_sel_hi:[1,0]
	v_add_f32_dpp v230, v227, v226 row_ror:8 row_mask:0xf bank_mask:0xf
	v_pk_mul_f32 v[234:235], v[100:101], v[92:93] op_sel:[0,1]
	v_pk_mul_f32 v[236:237], v[100:101], v[94:95] op_sel_hi:[1,0]
	v_add_f32_dpp v230, v230, v230 quad_perm:[1,0,3,2] row_mask:0xf bank_mask:0xf
	v_pk_mul_f32 v[238:239], v[100:101], v[94:95] op_sel:[0,1]
	ds_read_b128 v[222:225], v240 offset:41616
	v_add_f32_dpp v230, v230, v230 quad_perm:[2,3,0,1] row_mask:0xf bank_mask:0xf
	v_pk_fma_f32 v[232:233], v[206:207], v[80:81], v[232:233] op_sel_hi:[1,0,1]
	v_pk_fma_f32 v[234:235], v[208:209], v[80:81], v[234:235] op_sel:[0,1,0]
	v_add_f32_dpp v230, v230, v230 row_half_mirror row_mask:0xf bank_mask:0xf
	v_pk_fma_f32 v[236:237], v[210:211], v[82:83], v[236:237] op_sel_hi:[1,0,1]
	v_pk_fma_f32 v[238:239], v[212:213], v[82:83], v[238:239] op_sel:[0,1,0]
	v_mov_b32_dpp v231, v230 row_ror:8 row_mask:0xf bank_mask:0xf
	ds_write_b64 v217, v[228:229] offset:4032
	v_pk_fma_f32 v[206:207], v[88:89], v[230:231], v[232:233] op_sel_hi:[0,1,1] neg_lo:[1,0,0] neg_hi:[1,0,0]
	v_pk_fma_f32 v[208:209], v[88:89], v[230:231], v[234:235] op_sel:[1,0,0] neg_lo:[1,0,0] neg_hi:[1,0,0]
	v_pk_fma_f32 v[210:211], v[90:91], v[230:231], v[236:237] op_sel_hi:[0,1,1] neg_lo:[1,0,0] neg_hi:[1,0,0]
	v_pk_fma_f32 v[212:213], v[90:91], v[230:231], v[238:239] op_sel:[1,0,0] neg_lo:[1,0,0] neg_hi:[1,0,0]
	ds_read_b128 v[84:87], v240 offset:15776
	ds_read_b64 v[100:101], v242 offset:50592
	ds_read_b128 v[92:95], v240 offset:33184
	ds_read_b128 v[80:83], v240 offset:7072
	ds_read_b128 v[88:91], v240 offset:24480
	s_waitcnt lgkmcnt(7)
; template <int CTRL> __device__ __forceinline__ float dppf(float x) { return __builtin_bit_cast(float, __builtin_amdgcn_update_dpp(0, __builtin_bit_cast(int, x), CTRL, 0xF, 0xF, false)); }
; __device__ __forceinline__ void phase_rwkv_scan(const Fr& F, int jr) {
;     ...
;                 for (int pg = 0; pg < 64; pg += 16) {
; #pragma unroll
;                     for (int pi = 0; pi < 16; ++pi) {
;                         const int p = pg + pi, pn = p < 63 ? p + 1 : 63;
;                         const f32x4 w4n = PW[pn * 16], k4n = PW[1024 + pn * 16], b4n = PW[2048 + pn * 16], d4n = PW[3072 + pn * 16], r4n = PR[pn * 16];
;                         const float vvn = PV[pn * 32];
;                         f32x2 t = S01 * k4.xy; t = S23 * k4.zw + t; float sa = t.x + t.y;
;                         sa += dppf<0x128>(sa);
;                         const f32x2 dv01 = d4.xy * vv, dv23 = d4.zw * vv;
;                         sa += dppf<0x124>(sa);
;                         const f32x2 e01 = S01 * w4.xy + dv01;
;                         sa += dppf<0x122>(sa);
;                         const f32x2 e23 = S23 * w4.zw + dv23;
;                         sa += dppf<0x121>(sa);
;                         S01 = e01 - b4.xy * sa; S23 = e23 - b4.zw * sa;
;                         f32x2 u = S01 * r4.xy; u = S23 * r4.zw + u;
;                         PY[pi * 64] = u.x + u.y;
;                         w4 = w4n; k4 = k4n; b4 = b4n; d4 = d4n; r4 = r4n; vv = vvn;
;                     }
	v_pk_mul_f32 v[226:227], v[206:207], v[106:107] op_sel_hi:[1,0]
	v_pk_mul_f32 v[228:229], v[206:207], v[96:97] op_sel_hi:[1,0]
	v_pk_fma_f32 v[226:227], v[208:209], v[106:107], v[226:227] op_sel:[0,1,0]
	v_pk_fma_f32 v[228:229], v[208:209], v[96:97], v[228:229] op_sel:[0,1,0]
	v_pk_fma_f32 v[226:227], v[210:211], v[108:109], v[226:227] op_sel_hi:[1,0,1]
	v_pk_fma_f32 v[228:229], v[210:211], v[98:99], v[228:229] op_sel_hi:[1,0,1]
	v_pk_fma_f32 v[226:227], v[212:213], v[108:109], v[226:227] op_sel:[0,1,0]
	v_pk_fma_f32 v[228:229], v[212:213], v[98:99], v[228:229] op_sel:[0,1,0]
	v_pk_mul_f32 v[232:233], v[118:119], v[114:115] op_sel_hi:[1,0]
	v_add_f32_dpp v230, v227, v226 row_ror:8 row_mask:0xf bank_mask:0xf
	v_pk_mul_f32 v[234:235], v[118:119], v[114:115] op_sel:[0,1]
	v_pk_mul_f32 v[236:237], v[118:119], v[116:117] op_sel_hi:[1,0]
	v_add_f32_dpp v230, v230, v230 quad_perm:[1,0,3,2] row_mask:0xf bank_mask:0xf
	v_pk_mul_f32 v[238:239], v[118:119], v[116:117] op_sel:[0,1]
	ds_read_b128 v[96:99], v240 offset:41888
	v_add_f32_dpp v230, v230, v230 quad_perm:[2,3,0,1] row_mask:0xf bank_mask:0xf
	v_pk_fma_f32 v[232:233], v[206:207], v[102:103], v[232:233] op_sel_hi:[1,0,1]
	v_pk_fma_f32 v[234:235], v[208:209], v[102:103], v[234:235] op_sel:[0,1,0]
	v_add_f32_dpp v230, v230, v230 row_half_mirror row_mask:0xf bank_mask:0xf
	v_pk_fma_f32 v[236:237], v[210:211], v[104:105], v[236:237] op_sel_hi:[1,0,1]
	v_pk_fma_f32 v[238:239], v[212:213], v[104:105], v[238:239] op_sel:[0,1,0]
	v_mov_b32_dpp v231, v230 row_ror:8 row_mask:0xf bank_mask:0xf
	ds_write_b64 v217, v[228:229] offset:4608
	v_pk_fma_f32 v[206:207], v[110:111], v[230:231], v[232:233] op_sel_hi:[0,1,1] neg_lo:[1,0,0] neg_hi:[1,0,0]
	v_pk_fma_f32 v[208:209], v[110:111], v[230:231], v[234:235] op_sel:[1,0,0] neg_lo:[1,0,0] neg_hi:[1,0,0]
	v_pk_fma_f32 v[210:211], v[112:113], v[230:231], v[236:237] op_sel_hi:[0,1,1] neg_lo:[1,0,0] neg_hi:[1,0,0]
	v_pk_fma_f32 v[212:213], v[112:113], v[230:231], v[238:239] op_sel:[1,0,0] neg_lo:[1,0,0] neg_hi:[1,0,0]
	ds_read_b128 v[106:109], v240 offset:16048
	ds_read_b64 v[118:119], v242 offset:50864
	ds_read_b128 v[114:117], v240 offset:33456
	ds_read_b128 v[102:105], v240 offset:7344
	ds_read_b128 v[110:113], v240 offset:24752
	s_waitcnt lgkmcnt(7)
	v_pk_mul_f32 v[226:227], v[206:207], v[84:85] op_sel_hi:[1,0]
	v_pk_mul_f32 v[228:229], v[206:207], v[222:223] op_sel_hi:[1,0]
	v_pk_fma_f32 v[226:227], v[208:209], v[84:85], v[226:227] op_sel:[0,1,0]
	v_pk_fma_f32 v[228:229], v[208:209], v[222:223], v[228:229] op_sel:[0,1,0]
	v_pk_fma_f32 v[226:227], v[210:211], v[86:87], v[226:227] op_sel_hi:[1,0,1]
	v_pk_fma_f32 v[228:229], v[210:211], v[224:225], v[228:229] op_sel_hi:[1,0,1]
	v_pk_fma_f32 v[226:227], v[212:213], v[86:87], v[226:227] op_sel:[0,1,0]
	v_pk_fma_f32 v[228:229], v[212:213], v[224:225], v[228:229] op_sel:[0,1,0]
	v_pk_mul_f32 v[232:233], v[100:101], v[92:93] op_sel_hi:[1,0]
	v_add_f32_dpp v230, v227, v226 row_ror:8 row_mask:0xf bank_mask:0xf
	v_pk_mul_f32 v[234:235], v[100:101], v[92:93] op_sel:[0,1]
	v_pk_mul_f32 v[236:237], v[100:101], v[94:95] op_sel_hi:[1,0]
	v_add_f32_dpp v230, v230, v230 quad_perm:[1,0,3,2] row_mask:0xf bank_mask:0xf
	v_pk_mul_f32 v[238:239], v[100:101], v[94:95] op_sel:[0,1]
	ds_read_b128 v[222:225], v240 offset:42160
	v_add_f32_dpp v230, v230, v230 quad_perm:[2,3,0,1] row_mask:0xf bank_mask:0xf
	v_pk_fma_f32 v[232:233], v[206:207], v[80:81], v[232:233] op_sel_hi:[1,0,1]
	v_pk_fma_f32 v[234:235], v[208:209], v[80:81], v[234:235] op_sel:[0,1,0]
	v_add_f32_dpp v230, v230, v230 row_half_mirror row_mask:0xf bank_mask:0xf
	v_pk_fma_f32 v[236:237], v[210:211], v[82:83], v[236:237] op_sel_hi:[1,0,1]
	v_pk_fma_f32 v[238:239], v[212:213], v[82:83], v[238:239] op_sel:[0,1,0]
	v_mov_b32_dpp v231, v230 row_ror:8 row_mask:0xf bank_mask:0xf
	ds_write_b64 v217, v[228:229] offset:5184
	v_pk_fma_f32 v[206:207], v[88:89], v[230:231], v[232:233] op_sel_hi:[0,1,1] neg_lo:[1,0,0] neg_hi:[1,0,0]
	v_pk_fma_f32 v[208:209], v[88:89], v[230:231], v[234:235] op_sel:[1,0,0] neg_lo:[1,0,0] neg_hi:[1,0,0]
	v_pk_fma_f32 v[210:211], v[90:91], v[230:231], v[236:237] op_sel_hi:[0,1,1] neg_lo:[1,0,0] neg_hi:[1,0,0]
	v_pk_fma_f32 v[212:213], v[90:91], v[230:231], v[238:239] op_sel:[1,0,0] neg_lo:[1,0,0] neg_hi:[1,0,0]
	ds_read_b128 v[84:87], v240 offset:16320
	ds_read_b64 v[100:101], v242 offset:51136
	ds_read_b128 v[92:95], v240 offset:33728
	ds_read_b128 v[80:83], v240 offset:7616
	ds_read_b128 v[88:91], v240 offset:25024
	s_waitcnt lgkmcnt(7)
; template <int CTRL> __device__ __forceinline__ float dppf(float x) { return __builtin_bit_cast(float, __builtin_amdgcn_update_dpp(0, __builtin_bit_cast(int, x), CTRL, 0xF, 0xF, false)); }
; __device__ __forceinline__ void phase_rwkv_scan(const Fr& F, int jr) {
;     ...
;                 for (int pg = 0; pg < 64; pg += 16) {
; #pragma unroll
;                     for (int pi = 0; pi < 16; ++pi) {
;                         const int p = pg + pi, pn = p < 63 ? p + 1 : 63;
;                         const f32x4 w4n = PW[pn * 16], k4n = PW[1024 + pn * 16], b4n = PW[2048 + pn * 16], d4n = PW[3072 + pn * 16], r4n = PR[pn * 16];
;                         const float vvn = PV[pn * 32];
;                         f32x2 t = S01 * k4.xy; t = S23 * k4.zw + t; float sa = t.x + t.y;
;                         sa += dppf<0x128>(sa);
;                         const f32x2 dv01 = d4.xy * vv, dv23 = d4.zw * vv;
;                         sa += dppf<0x124>(sa);
;                         const f32x2 e01 = S01 * w4.xy + dv01;
;                         sa += dppf<0x122>(sa);
;                         const f32x2 e23 = S23 * w4.zw + dv23;
;                         sa += dppf<0x121>(sa);
;                         S01 = e01 - b4.xy * sa; S23 = e23 - b4.zw * sa;
;                         f32x2 u = S01 * r4.xy; u = S23 * r4.zw + u;
;                         PY[pi * 64] = u.x + u.y;
;                         w4 = w4n; k4 = k4n; b4 = b4n; d4 = d4n; r4 = r4n; vv = vvn;
;                     }
	v_pk_mul_f32 v[226:227], v[206:207], v[106:107] op_sel_hi:[1,0]
	v_pk_mul_f32 v[228:229], v[206:207], v[96:97] op_sel_hi:[1,0]
	v_pk_fma_f32 v[226:227], v[208:209], v[106:107], v[226:227] op_sel:[0,1,0]
	v_pk_fma_f32 v[228:229], v[208:209], v[96:97], v[228:229] op_sel:[0,1,0]
	v_pk_fma_f32 v[226:227], v[210:211], v[108:109], v[226:227] op_sel_hi:[1,0,1]
	v_pk_fma_f32 v[228:229], v[210:211], v[98:99], v[228:229] op_sel_hi:[1,0,1]
	v_pk_fma_f32 v[226:227], v[212:213], v[108:109], v[226:227] op_sel:[0,1,0]
	v_pk_fma_f32 v[228:229], v[212:213], v[98:99], v[228:229] op_sel:[0,1,0]
	v_pk_mul_f32 v[232:233], v[118:119], v[114:115] op_sel_hi:[1,0]
	v_add_f32_dpp v230, v227, v226 row_ror:8 row_mask:0xf bank_mask:0xf
	v_pk_mul_f32 v[234:235], v[118:119], v[114:115] op_sel:[0,1]
	v_pk_mul_f32 v[236:237], v[118:119], v[116:117] op_sel_hi:[1,0]
	v_add_f32_dpp v230, v230, v230 quad_perm:[1,0,3,2] row_mask:0xf bank_mask:0xf
	v_pk_mul_f32 v[238:239], v[118:119], v[116:117] op_sel:[0,1]
	ds_read_b128 v[96:99], v240 offset:42432
	v_add_f32_dpp v230, v230, v230 quad_perm:[2,3,0,1] row_mask:0xf bank_mask:0xf
	v_pk_fma_f32 v[232:233], v[206:207], v[102:103], v[232:233] op_sel_hi:[1,0,1]
	v_pk_fma_f32 v[234:235], v[208:209], v[102:103], v[234:235] op_sel:[0,1,0]
	v_add_f32_dpp v230, v230, v230 row_half_mirror row_mask:0xf bank_mask:0xf
	v_pk_fma_f32 v[236:237], v[210:211], v[104:105], v[236:237] op_sel_hi:[1,0,1]
	v_pk_fma_f32 v[238:239], v[212:213], v[104:105], v[238:239] op_sel:[0,1,0]
	v_mov_b32_dpp v231, v230 row_ror:8 row_mask:0xf bank_mask:0xf
	ds_write_b64 v217, v[228:229] offset:5760
	v_pk_fma_f32 v[206:207], v[110:111], v[230:231], v[232:233] op_sel_hi:[0,1,1] neg_lo:[1,0,0] neg_hi:[1,0,0]
	v_pk_fma_f32 v[208:209], v[110:111], v[230:231], v[234:235] op_sel:[1,0,0] neg_lo:[1,0,0] neg_hi:[1,0,0]
	v_pk_fma_f32 v[210:211], v[112:113], v[230:231], v[236:237] op_sel_hi:[0,1,1] neg_lo:[1,0,0] neg_hi:[1,0,0]
	v_pk_fma_f32 v[212:213], v[112:113], v[230:231], v[238:239] op_sel:[1,0,0] neg_lo:[1,0,0] neg_hi:[1,0,0]
	ds_read_b128 v[106:109], v240 offset:16592
	ds_read_b64 v[118:119], v242 offset:51408
	ds_read_b128 v[114:117], v240 offset:34000
	ds_read_b128 v[102:105], v240 offset:7888
	ds_read_b128 v[110:113], v240 offset:25296
	s_waitcnt lgkmcnt(7)
	v_pk_mul_f32 v[226:227], v[206:207], v[84:85] op_sel_hi:[1,0]
	v_pk_mul_f32 v[228:229], v[206:207], v[222:223] op_sel_hi:[1,0]
	v_pk_fma_f32 v[226:227], v[208:209], v[84:85], v[226:227] op_sel:[0,1,0]
	v_pk_fma_f32 v[228:229], v[208:209], v[222:223], v[228:229] op_sel:[0,1,0]
	v_pk_fma_f32 v[226:227], v[210:211], v[86:87], v[226:227] op_sel_hi:[1,0,1]
	v_pk_fma_f32 v[228:229], v[210:211], v[224:225], v[228:229] op_sel_hi:[1,0,1]
	v_pk_fma_f32 v[226:227], v[212:213], v[86:87], v[226:227] op_sel:[0,1,0]
	v_pk_fma_f32 v[228:229], v[212:213], v[224:225], v[228:229] op_sel:[0,1,0]
	v_pk_mul_f32 v[232:233], v[100:101], v[92:93] op_sel_hi:[1,0]
	v_add_f32_dpp v230, v227, v226 row_ror:8 row_mask:0xf bank_mask:0xf
	v_pk_mul_f32 v[234:235], v[100:101], v[92:93] op_sel:[0,1]
	v_pk_mul_f32 v[236:237], v[100:101], v[94:95] op_sel_hi:[1,0]
	v_add_f32_dpp v230, v230, v230 quad_perm:[1,0,3,2] row_mask:0xf bank_mask:0xf
	v_pk_mul_f32 v[238:239], v[100:101], v[94:95] op_sel:[0,1]
	ds_read_b128 v[222:225], v240 offset:42704
	v_add_f32_dpp v230, v230, v230 quad_perm:[2,3,0,1] row_mask:0xf bank_mask:0xf
	v_pk_fma_f32 v[232:233], v[206:207], v[80:81], v[232:233] op_sel_hi:[1,0,1]
	v_pk_fma_f32 v[234:235], v[208:209], v[80:81], v[234:235] op_sel:[0,1,0]
	v_add_f32_dpp v230, v230, v230 row_half_mirror row_mask:0xf bank_mask:0xf
	v_pk_fma_f32 v[236:237], v[210:211], v[82:83], v[236:237] op_sel_hi:[1,0,1]
	v_pk_fma_f32 v[238:239], v[212:213], v[82:83], v[238:239] op_sel:[0,1,0]
	v_mov_b32_dpp v231, v230 row_ror:8 row_mask:0xf bank_mask:0xf
	ds_write_b64 v217, v[228:229] offset:6336
	v_pk_fma_f32 v[206:207], v[88:89], v[230:231], v[232:233] op_sel_hi:[0,1,1] neg_lo:[1,0,0] neg_hi:[1,0,0]
	v_pk_fma_f32 v[208:209], v[88:89], v[230:231], v[234:235] op_sel:[1,0,0] neg_lo:[1,0,0] neg_hi:[1,0,0]
	v_pk_fma_f32 v[210:211], v[90:91], v[230:231], v[236:237] op_sel_hi:[0,1,1] neg_lo:[1,0,0] neg_hi:[1,0,0]
	v_pk_fma_f32 v[212:213], v[90:91], v[230:231], v[238:239] op_sel:[1,0,0] neg_lo:[1,0,0] neg_hi:[1,0,0]
	ds_read_b128 v[84:87], v240 offset:16864
	ds_read_b64 v[100:101], v242 offset:51680
	ds_read_b128 v[92:95], v240 offset:34272
	ds_read_b128 v[80:83], v240 offset:8160
	ds_read_b128 v[88:91], v240 offset:25568
	s_waitcnt lgkmcnt(7)
; __device__ __forceinline__ unsigned f2bf(float f) { unsigned u = __builtin_bit_cast(unsigned, f); return (u + 0x7fffu + ((u >> 16) & 1u)) >> 16; }
; __device__ __forceinline__ void phase_rwkv_scan(const Fr& F, int jr) {
;     ...
;                 for (int pg = 0; pg < 64; pg += 16) {
; #pragma unroll
;                     for (int pi = 0; pi < 16; ++pi) {
;                         const int p = pg + pi, pn = p < 63 ? p + 1 : 63;
;                         const f32x4 w4n = PW[pn * 16], k4n = PW[1024 + pn * 16], b4n = PW[2048 + pn * 16], d4n = PW[3072 + pn * 16], r4n = PR[pn * 16];
;                         const float vvn = PV[pn * 32];
;                         f32x2 t = S01 * k4.xy; t = S23 * k4.zw + t; float sa = t.x + t.y;
;                         sa += dppf<0x128>(sa);
;                         const f32x2 dv01 = d4.xy * vv, dv23 = d4.zw * vv;
;                         sa += dppf<0x124>(sa);
;                         const f32x2 e01 = S01 * w4.xy + dv01;
;                         sa += dppf<0x122>(sa);
;                         const f32x2 e23 = S23 * w4.zw + dv23;
;                         sa += dppf<0x121>(sa);
;                         S01 = e01 - b4.xy * sa; S23 = e23 - b4.zw * sa;
;                         f32x2 u = S01 * r4.xy; u = S23 * r4.zw + u;
;                         PY[pi * 64] = u.x + u.y;
;                         w4 = w4n; k4 = k4n; b4 = b4n; d4 = d4n; r4 = r4n; vv = vvn;
;                     }
;                     asm volatile("s_waitcnt lgkmcnt(0)" ::: "memory");
;                     {
;                         const int j = lane >> 2, q = lane & 3; const float* yp = Ypw + j * 64 + q * 16;
;                         const f32x4 a0 = *(const f32x4*)yp, a1 = *(const f32x4*)(yp + 4), a2 = *(const f32x4*)(yp + 8), a3 = *(const f32x4*)(yp + 12);
;                         const f32x4 ssum = (a0 + a1) + (a2 + a3); const float yv = (ssum.x + ssum.y) + (ssum.z + ssum.w);
;                         const size_t row = (size_t)b * TB + tokof(s, chunk * 64 + pg + j);
;                         Yb[row * D + h * 64 + 32 * half + 4 * wave + q] = (bf16)f2bf(yv);
;                     }
;                     asm volatile("s_waitcnt lgkmcnt(0)" ::: "memory");
;                 }
	v_pk_mul_f32 v[226:227], v[206:207], v[106:107] op_sel_hi:[1,0]
	v_pk_mul_f32 v[228:229], v[206:207], v[96:97] op_sel_hi:[1,0]
	v_pk_fma_f32 v[226:227], v[208:209], v[106:107], v[226:227] op_sel:[0,1,0]
	v_pk_fma_f32 v[228:229], v[208:209], v[96:97], v[228:229] op_sel:[0,1,0]
	v_pk_fma_f32 v[226:227], v[210:211], v[108:109], v[226:227] op_sel_hi:[1,0,1]
	v_pk_fma_f32 v[228:229], v[210:211], v[98:99], v[228:229] op_sel_hi:[1,0,1]
	v_pk_fma_f32 v[226:227], v[212:213], v[108:109], v[226:227] op_sel:[0,1,0]
	v_pk_fma_f32 v[228:229], v[212:213], v[98:99], v[228:229] op_sel:[0,1,0]
	v_pk_mul_f32 v[232:233], v[118:119], v[114:115] op_sel_hi:[1,0]
	v_add_f32_dpp v230, v227, v226 row_ror:8 row_mask:0xf bank_mask:0xf
	v_pk_mul_f32 v[234:235], v[118:119], v[114:115] op_sel:[0,1]
	v_pk_mul_f32 v[236:237], v[118:119], v[116:117] op_sel_hi:[1,0]
	v_add_f32_dpp v230, v230, v230 quad_perm:[1,0,3,2] row_mask:0xf bank_mask:0xf
	v_pk_mul_f32 v[238:239], v[118:119], v[116:117] op_sel:[0,1]
	ds_read_b128 v[96:99], v240 offset:42976
	v_add_f32_dpp v230, v230, v230 quad_perm:[2,3,0,1] row_mask:0xf bank_mask:0xf
	v_pk_fma_f32 v[232:233], v[206:207], v[102:103], v[232:233] op_sel_hi:[1,0,1]
	v_pk_fma_f32 v[234:235], v[208:209], v[102:103], v[234:235] op_sel:[0,1,0]
	v_add_f32_dpp v230, v230, v230 row_half_mirror row_mask:0xf bank_mask:0xf
	v_pk_fma_f32 v[236:237], v[210:211], v[104:105], v[236:237] op_sel_hi:[1,0,1]
	v_pk_fma_f32 v[238:239], v[212:213], v[104:105], v[238:239] op_sel:[0,1,0]
	v_mov_b32_dpp v231, v230 row_ror:8 row_mask:0xf bank_mask:0xf
	ds_write_b64 v217, v[228:229] offset:6912
	v_pk_fma_f32 v[206:207], v[110:111], v[230:231], v[232:233] op_sel_hi:[0,1,1] neg_lo:[1,0,0] neg_hi:[1,0,0]
	v_pk_fma_f32 v[208:209], v[110:111], v[230:231], v[234:235] op_sel:[1,0,0] neg_lo:[1,0,0] neg_hi:[1,0,0]
	v_pk_fma_f32 v[210:211], v[112:113], v[230:231], v[236:237] op_sel_hi:[0,1,1] neg_lo:[1,0,0] neg_hi:[1,0,0]
	v_pk_fma_f32 v[212:213], v[112:113], v[230:231], v[238:239] op_sel:[1,0,0] neg_lo:[1,0,0] neg_hi:[1,0,0]
	ds_read_b128 v[106:109], v240 offset:17136
	ds_read_b64 v[118:119], v242 offset:51952
	ds_read_b128 v[114:117], v240 offset:34544
	ds_read_b128 v[102:105], v240 offset:8432
	ds_read_b128 v[110:113], v240 offset:25840
	s_waitcnt lgkmcnt(7)
	v_pk_mul_f32 v[226:227], v[206:207], v[84:85] op_sel_hi:[1,0]
	v_pk_mul_f32 v[228:229], v[206:207], v[222:223] op_sel_hi:[1,0]
	v_pk_fma_f32 v[226:227], v[208:209], v[84:85], v[226:227] op_sel:[0,1,0]
	v_pk_fma_f32 v[228:229], v[208:209], v[222:223], v[228:229] op_sel:[0,1,0]
	v_pk_fma_f32 v[226:227], v[210:211], v[86:87], v[226:227] op_sel_hi:[1,0,1]
	v_pk_fma_f32 v[228:229], v[210:211], v[224:225], v[228:229] op_sel_hi:[1,0,1]
	v_pk_fma_f32 v[226:227], v[212:213], v[86:87], v[226:227] op_sel:[0,1,0]
	v_pk_fma_f32 v[228:229], v[212:213], v[224:225], v[228:229] op_sel:[0,1,0]
	v_pk_mul_f32 v[232:233], v[100:101], v[92:93] op_sel_hi:[1,0]
	v_add_f32_dpp v230, v227, v226 row_ror:8 row_mask:0xf bank_mask:0xf
	v_pk_mul_f32 v[234:235], v[100:101], v[92:93] op_sel:[0,1]
	v_pk_mul_f32 v[236:237], v[100:101], v[94:95] op_sel_hi:[1,0]
	v_add_f32_dpp v230, v230, v230 quad_perm:[1,0,3,2] row_mask:0xf bank_mask:0xf
	v_pk_mul_f32 v[238:239], v[100:101], v[94:95] op_sel:[0,1]
	ds_read_b128 v[222:225], v240 offset:43248
	v_add_f32_dpp v230, v230, v230 quad_perm:[2,3,0,1] row_mask:0xf bank_mask:0xf
	v_pk_fma_f32 v[232:233], v[206:207], v[80:81], v[232:233] op_sel_hi:[1,0,1]
	v_pk_fma_f32 v[234:235], v[208:209], v[80:81], v[234:235] op_sel:[0,1,0]
	v_add_f32_dpp v230, v230, v230 row_half_mirror row_mask:0xf bank_mask:0xf
	v_pk_fma_f32 v[236:237], v[210:211], v[82:83], v[236:237] op_sel_hi:[1,0,1]
	v_pk_fma_f32 v[238:239], v[212:213], v[82:83], v[238:239] op_sel:[0,1,0]
	v_mov_b32_dpp v231, v230 row_ror:8 row_mask:0xf bank_mask:0xf
	ds_write_b64 v217, v[228:229] offset:7488
	v_pk_fma_f32 v[206:207], v[88:89], v[230:231], v[232:233] op_sel_hi:[0,1,1] neg_lo:[1,0,0] neg_hi:[1,0,0]
	v_pk_fma_f32 v[208:209], v[88:89], v[230:231], v[234:235] op_sel:[1,0,0] neg_lo:[1,0,0] neg_hi:[1,0,0]
	v_pk_fma_f32 v[210:211], v[90:91], v[230:231], v[236:237] op_sel_hi:[0,1,1] neg_lo:[1,0,0] neg_hi:[1,0,0]
	v_pk_fma_f32 v[212:213], v[90:91], v[230:231], v[238:239] op_sel:[1,0,0] neg_lo:[1,0,0] neg_hi:[1,0,0]
	s_waitcnt lgkmcnt(2)
	v_pk_mul_f32 v[226:227], v[206:207], v[106:107] op_sel_hi:[1,0]
	v_pk_mul_f32 v[228:229], v[206:207], v[96:97] op_sel_hi:[1,0]
	v_pk_fma_f32 v[226:227], v[208:209], v[106:107], v[226:227] op_sel:[0,1,0]
	v_pk_fma_f32 v[228:229], v[208:209], v[96:97], v[228:229] op_sel:[0,1,0]
	v_pk_fma_f32 v[226:227], v[210:211], v[108:109], v[226:227] op_sel_hi:[1,0,1]
	v_pk_fma_f32 v[228:229], v[210:211], v[98:99], v[228:229] op_sel_hi:[1,0,1]
	v_pk_fma_f32 v[226:227], v[212:213], v[108:109], v[226:227] op_sel:[0,1,0]
	v_pk_fma_f32 v[228:229], v[212:213], v[98:99], v[228:229] op_sel:[0,1,0]
	v_pk_mul_f32 v[232:233], v[118:119], v[114:115] op_sel_hi:[1,0]
	v_add_f32_dpp v230, v227, v226 row_ror:8 row_mask:0xf bank_mask:0xf
	v_pk_mul_f32 v[234:235], v[118:119], v[114:115] op_sel:[0,1]
	v_pk_mul_f32 v[236:237], v[118:119], v[116:117] op_sel_hi:[1,0]
	v_add_f32_dpp v230, v230, v230 quad_perm:[1,0,3,2] row_mask:0xf bank_mask:0xf
	v_pk_mul_f32 v[238:239], v[118:119], v[116:117] op_sel:[0,1]
	s_nop 0
	v_add_f32_dpp v230, v230, v230 quad_perm:[2,3,0,1] row_mask:0xf bank_mask:0xf
	v_pk_fma_f32 v[232:233], v[206:207], v[102:103], v[232:233] op_sel_hi:[1,0,1]
	v_pk_fma_f32 v[234:235], v[208:209], v[102:103], v[234:235] op_sel:[0,1,0]
	v_add_f32_dpp v230, v230, v230 row_half_mirror row_mask:0xf bank_mask:0xf
	v_pk_fma_f32 v[236:237], v[210:211], v[104:105], v[236:237] op_sel_hi:[1,0,1]
	v_pk_fma_f32 v[238:239], v[212:213], v[104:105], v[238:239] op_sel:[0,1,0]
	v_mov_b32_dpp v231, v230 row_ror:8 row_mask:0xf bank_mask:0xf
	ds_write_b64 v217, v[228:229] offset:8064
	v_pk_fma_f32 v[206:207], v[110:111], v[230:231], v[232:233] op_sel_hi:[0,1,1] neg_lo:[1,0,0] neg_hi:[1,0,0]
	v_pk_fma_f32 v[208:209], v[110:111], v[230:231], v[234:235] op_sel:[1,0,0] neg_lo:[1,0,0] neg_hi:[1,0,0]
	v_pk_fma_f32 v[210:211], v[112:113], v[230:231], v[236:237] op_sel_hi:[0,1,1] neg_lo:[1,0,0] neg_hi:[1,0,0]
	v_pk_fma_f32 v[212:213], v[112:113], v[230:231], v[238:239] op_sel:[1,0,0] neg_lo:[1,0,0] neg_hi:[1,0,0]
	s_add_i32 s10, s10, 1
	s_xor_b32 s11, s11, 0xcc00
	s_waitcnt lgkmcnt(0)
	s_barrier
; __device__ __forceinline__ unsigned f2bf(float f) { unsigned u = __builtin_bit_cast(unsigned, f); return (u + 0x7fffu + ((u >> 16) & 1u)) >> 16; }
; __device__ __forceinline__ void phase_rwkv_scan(const Fr& F, int jr) {
;     ...
;                         f32x2 u = S01 * r4.xy; u = S23 * r4.zw + u;
;                         PY[pi * 64] = u.x + u.y;
;                         w4 = w4n; k4 = k4n; b4 = b4n; d4 = d4n; r4 = r4n; vv = vvn;
;                     }
;                     asm volatile("s_waitcnt lgkmcnt(0)" ::: "memory");
;                     {
;                         const int j = lane >> 2, q = lane & 3; const float* yp = Ypw + j * 64 + q * 16;
;                         const f32x4 a0 = *(const f32x4*)yp, a1 = *(const f32x4*)(yp + 4), a2 = *(const f32x4*)(yp + 8), a3 = *(const f32x4*)(yp + 12);
;                         const f32x4 ssum = (a0 + a1) + (a2 + a3); const float yv = (ssum.x + ssum.y) + (ssum.z + ssum.w);
;                         const size_t row = (size_t)b * TB + tokof(s, chunk * 64 + pg + j);
;                         Yb[row * D + h * 64 + 32 * half + 4 * wave + q] = (bf16)f2bf(yv);
;                     }
;                     asm volatile("s_waitcnt lgkmcnt(0)" ::: "memory");
	s_cmp_lt_u32 s10, 136
	s_cbranch_scc1 .Lrw0_shc
	v_pk_mul_f32 v[228:229], v[206:207], v[222:223] op_sel_hi:[1,0]
	v_pk_fma_f32 v[228:229], v[208:209], v[222:223], v[228:229] op_sel:[0,1,0]
	v_pk_fma_f32 v[228:229], v[210:211], v[224:225], v[228:229] op_sel_hi:[1,0,1]
	v_pk_fma_f32 v[228:229], v[212:213], v[224:225], v[228:229] op_sel:[0,1,0]
	s_mov_b32 s87, s15
	s_nop 0
	ds_write_b64 v217, v[228:229] offset:8640
	ds_read_b128 v[0:3], v218 offset:0
	ds_read_b128 v[4:7], v218 offset:16
	ds_read_b128 v[8:11], v218 offset:32
	ds_read_b128 v[12:15], v218 offset:48
	ds_read_b128 v[16:19], v218 offset:64
	ds_read_b128 v[20:23], v218 offset:80
	ds_read_b128 v[24:27], v218 offset:96
	ds_read_b128 v[28:31], v218 offset:112
	s_waitcnt lgkmcnt(6)
	v_pk_add_f32 v[0:1], v[0:1], v[2:3]
	s_nop 0
	v_pk_add_f32 v[4:5], v[4:5], v[6:7]
	s_nop 0
	s_waitcnt lgkmcnt(4)
	v_pk_add_f32 v[8:9], v[8:9], v[10:11]
	s_nop 0
	v_pk_add_f32 v[12:13], v[12:13], v[14:15]
	s_nop 0
	v_pk_add_f32 v[0:1], v[0:1], v[4:5]
	s_nop 0
	s_waitcnt lgkmcnt(2)
	v_pk_add_f32 v[16:17], v[16:17], v[18:19]
	s_nop 0
	v_pk_add_f32 v[20:21], v[20:21], v[22:23]
	s_nop 0
	v_pk_add_f32 v[8:9], v[8:9], v[12:13]
	s_nop 0
	s_waitcnt lgkmcnt(0)
	v_pk_add_f32 v[24:25], v[24:25], v[26:27]
	s_nop 0
	v_pk_add_f32 v[28:29], v[28:29], v[30:31]
	s_nop 0
	v_pk_add_f32 v[16:17], v[16:17], v[20:21]
	s_nop 0
	v_pk_add_f32 v[0:1], v[0:1], v[8:9]
	s_nop 0
	v_pk_add_f32 v[24:25], v[24:25], v[28:29]
	s_nop 0
	v_add_u32_e32 v243, s87, v219
	s_nop 0
	v_pk_add_f32 v[16:17], v[16:17], v[24:25]
	s_nop 0
	v_lshl_add_u32 v243, v243, 11, v220
	s_nop 0
	v_pk_add_f32 v[0:1], v[0:1], v[16:17] op_sel:[0,1] op_sel_hi:[1,0]
	s_nop 0
	s_nop 0
	s_nop 0
	v_cvt_pk_bf16_f32 v244, v0, v1
	s_nop 0
	s_nop 0
	global_store_dword v243, v244, s[20:21]
	s_nop 0
	s_setprio 0
	s_branch .Lrw0_end
